# in-projection last partial round: the 12 left-over units are split into 128x128 blocks over workgroups 0..47, each running a dedicated single-block K loop (4-slot LDS ring); weight conversion moves to
# speedup vs baseline: 1.0118x; 1.0023x over previous
.LBB0_6:
	s_load_dwordx2 s[18:19], s[0:1], 0xc0
	s_lshl_b32 s2, s93, 3
	v_writelane_b32 v252, s2, 4
	s_load_dwordx16 s[60:75], s[0:1], 0x40
	v_mov_b32_e32 v203, 0x358637bd
	s_waitcnt lgkmcnt(0)
	s_lshl_b32 s33, s18, 3
	s_add_u32 s2, s8, 0x6204000
	s_addc_u32 s3, s9, 0
	v_writelane_b32 v252, s2, 5
	s_lshl_b32 s96, s18, 5
	v_mov_b32_e32 v204, 0x3c0881c4
	v_writelane_b32 v252, s3, 6
	v_writelane_b32 v252, s20, 7
	v_mov_b32_e32 v205, 0xbab64f3b
	v_mov_b32_e32 v206, 1
	v_writelane_b32 v252, s21, 8
	s_lshl_b32 s20, s93, 1
	s_cmpk_lt_i32 s20, 0x2180
	s_cselect_b64 s[2:3], -1, 0
	v_writelane_b32 v252, s2, 9
	v_mov_b32_e32 v215, 0x4000
	v_bfrev_b32_e32 v216, 0.5
	v_writelane_b32 v252, s3, 10
	s_add_u32 s2, s8, 0x16a94000
	s_addc_u32 s3, s9, 0
	s_add_u32 s46, s8, 0x4000
	v_writelane_b32 v252, s2, 11
	s_addc_u32 s47, s9, 0
	v_mov_b32_e32 v217, 0x3e000000
	v_writelane_b32 v252, s3, 12
	s_add_u32 s2, s8, 0x1304000
	s_addc_u32 s3, s9, 0
	v_writelane_b32 v252, s2, 13
	v_mov_b32_e32 v218, 0x4f
	v_mov_b32_e32 v219, 0x5f
	v_writelane_b32 v252, s3, 14
	s_add_u32 s2, s8, 0x804000
	s_addc_u32 s3, s9, 0
	v_writelane_b32 v252, s2, 15
	v_mov_b32_e32 v220, 0x6f
	v_mov_b32_e32 v221, 0xfffff500
	v_writelane_b32 v252, s3, 16
	s_add_u32 s2, s8, 0x604000
	s_addc_u32 s3, s9, 0
	s_lshl_b32 s48, s18, 1
	v_writelane_b32 v252, s2, 17
	s_add_u32 s44, s8, 0x16ac4000
	s_addc_u32 s45, s9, 0
	v_writelane_b32 v252, s3, 18
	s_lshl_b32 s2, s93, 9
	s_lshl_b32 s56, s18, 9
	v_writelane_b32 v252, s2, 19
	s_add_u32 s2, s8, 0xa304000
	s_addc_u32 s3, s9, 0
	v_writelane_b32 v252, s2, 20
	s_cmpk_lt_i32 s93, 0x100
	v_mov_b32_e32 v222, 0x7f800000
	v_writelane_b32 v252, s3, 21
	s_cselect_b64 s[2:3], -1, 0
	v_writelane_b32 v252, s2, 22
	v_not_b32_e32 v223, 63
	v_not_b32_e32 v224, 31
	v_writelane_b32 v252, s3, 23
	s_and_b32 s2, s93, 3
	v_writelane_b32 v252, s2, 24
	s_lshl_b32 s2, s93, 6
	s_and_b32 s2, s2, 0x3f00
	v_writelane_b32 v252, s2, 25
	s_ashr_i32 s2, s93, 31
	v_writelane_b32 v252, s2, 26
	s_lshr_b32 s2, s2, 29
	s_add_i32 s2, s93, s2
	s_ashr_i32 s21, s2, 3
	s_and_b32 s2, s2, -8
	s_sub_i32 s22, s93, s2
	s_lshl_b32 s3, s22, 5
	s_ashr_i32 s2, s18, 31
	s_add_u32 s12, s8, 0xc404000
	v_writelane_b32 v252, s2, 27
	s_addc_u32 s13, s9, 0
	v_writelane_b32 v252, s12, 28
	s_mul_hi_i32 s2, s93, 0x2aaaaaab
	v_mov_b32_e32 v225, 0x7fc00000
	v_writelane_b32 v252, s13, 29
	s_add_u32 s12, s8, 0x16acc000
	s_addc_u32 s13, s9, 0
	v_writelane_b32 v252, s12, 30
	s_movk_i32 s37, 0x4000
	s_mov_b32 s30, 0x18000
	v_writelane_b32 v252, s13, 31
	s_add_u32 s12, s8, 0x12da4000
	s_addc_u32 s13, s9, 0
	s_add_u32 s24, s8, 0x139d4000
	s_addc_u32 s25, s9, 0
	v_writelane_b32 v252, s12, 32
	s_add_u32 s94, s8, 0x15234000
	s_addc_u32 s95, s9, 0
	v_writelane_b32 v252, s13, 33
	s_lshr_b32 s12, s2, 31
	s_add_i32 s15, s2, s12
	s_mul_i32 s2, s15, 6
	s_sub_i32 s23, s93, s2
	s_lshl_b32 s16, s15, 8
	s_lshl_b32 s26, s23, 6
	s_add_i32 s2, s16, 0x100
	s_ashr_i32 s27, s26, 31
	s_cmpk_lt_i32 s93, 0x60
	s_cselect_b64 s[28:29], -1, 0
	v_writelane_b32 v252, s28, 34
	s_lshl_b32 s13, s15, 4
	s_addk_i32 s13, 0x4000
	v_writelane_b32 v252, s29, 35
	v_writelane_b32 v252, s13, 36
	s_sub_i32 s13, s18, s23
	s_add_i32 s13, s13, 5
	s_lshl_b64 s[28:29], s[26:27], 1
	v_writelane_b32 v252, s13, 37
	s_add_u32 s13, s8, s28
	v_writelane_b32 v252, s28, 38
	s_addc_u32 s17, s9, s29
	s_mul_i32 s12, s23, 0x208000
	v_writelane_b32 v252, s29, 39
	s_add_u32 s28, s13, 0xc404500
	s_addc_u32 s29, s17, 0
	v_writelane_b32 v252, s28, 40
	s_add_u32 s12, s8, s12
	s_mov_b32 s31, 0xc000
	v_writelane_b32 v252, s29, 41
	v_writelane_b32 v252, s26, 42
	s_mul_hi_i32 s13, s26, 0x8200
	s_addc_u32 s13, s9, s13
	s_add_u32 s12, s12, 0x12174000
	v_writelane_b32 v252, s27, 43
	s_addc_u32 s13, s13, 0
	v_writelane_b32 v252, s12, 44
	s_mov_b32 s36, 0x30000
	s_movk_i32 s57, 0x1700
	v_writelane_b32 v252, s13, 45
	s_ashr_i32 s12, s23, 31
	v_writelane_b32 v252, s12, 46
	s_cmpk_lt_i32 s93, 0x30c
	s_mul_i32 s12, s22, 0x61
	s_cselect_b64 s[26:27], -1, 0
	s_add_i32 s17, s12, 4
	v_writelane_b32 v252, s26, 47
	s_add_u32 s12, s8, 0x16ac8000
	s_addc_u32 s13, s9, 0
	v_writelane_b32 v252, s27, 48
	v_writelane_b32 v252, s12, 49
	s_movk_i32 s76, 0x104
	s_mov_b32 s77, 0x5c000
	v_writelane_b32 v252, s13, 50
	s_add_u32 s12, s8, 0x14604000
	s_addc_u32 s13, s9, 0
	v_writelane_b32 v252, s12, 51
	s_nop 1
	v_writelane_b32 v252, s13, 52
	s_mul_i32 s12, s18, -3
	s_addk_i32 s12, 0x30c
	s_cmp_eq_u32 s18, 0x100
	s_cselect_b32 s12, 48, s12
	s_cmp_gt_i32 s12, 0
	s_cselect_b64 s[26:27], -1, 0
	s_cmp_le_i32 s18, s12
	s_cselect_b64 s[28:29], -1, 0
	v_writelane_b32 v252, s28, 53
	s_cmp_lt_i32 s93, s12
	s_nop 0
	v_writelane_b32 v252, s29, 54
	s_cselect_b64 s[28:29], -1, 0
	s_sub_i32 s13, s93, s12
	v_writelane_b32 v252, s28, 55
	s_cmpk_lt_u32 s13, 0x2c0
	s_nop 0
	v_writelane_b32 v252, s29, 56
	s_cselect_b64 s[28:29], -1, 0
	v_writelane_b32 v252, s28, 57
	s_sub_i32 s13, s18, s12
	s_lshl_b32 s13, s13, 1
	v_writelane_b32 v252, s29, 58
	v_writelane_b32 v252, s13, 59
	s_cmp_gt_i32 s18, s12
	s_cselect_b64 s[12:13], -1, 0
	v_writelane_b32 v252, s26, 60
	s_and_b64 s[12:13], s[26:27], s[12:13]
	s_cmpk_lt_i32 s93, 0x2c0
	v_writelane_b32 v252, s27, 61
	v_writelane_b32 v252, s12, 62
	s_mov_b32 s28, 0x800000
	s_movk_i32 s29, 0x6000
	v_writelane_b32 v252, s13, 63
	s_cselect_b64 s[12:13], -1, 0
	v_writelane_b32 v253, s12, 0
	s_cmp_gt_i32 s11, 38
	s_nop 0
	v_writelane_b32 v253, s13, 1
	s_cselect_b64 s[12:13], -1, 0
	v_writelane_b32 v253, s12, 2
	s_nop 1
	v_writelane_b32 v253, s13, 3
	s_add_u32 s12, s8, 0x200
	s_addc_u32 s13, s9, 0
	v_writelane_b32 v253, s12, 4
	s_nop 1
	v_writelane_b32 v253, s13, 5
	s_add_u32 s12, s8, 0x1000
	s_addc_u32 s13, s9, 0
	v_writelane_b32 v253, s12, 6
	s_nop 1
	v_writelane_b32 v253, s13, 7
	s_add_u32 s12, s8, 0x1100
	s_addc_u32 s13, s9, 0
	v_writelane_b32 v253, s12, 8
	s_nop 1
	v_writelane_b32 v253, s13, 9
	s_add_u32 s12, s8, 0x1200
	s_addc_u32 s13, s9, 0
	v_writelane_b32 v253, s12, 10
	s_nop 1
	v_writelane_b32 v253, s13, 11
	s_add_u32 s12, s8, 0x1300
	s_addc_u32 s13, s9, 0
	v_writelane_b32 v253, s12, 12
	s_cmp_eq_u32 s14, 15
	s_nop 0
	v_writelane_b32 v253, s13, 13
	s_cselect_b64 s[12:13], -1, 0
	v_writelane_b32 v253, s12, 14
	s_cmp_eq_u32 s14, 14
	s_nop 0
	v_writelane_b32 v253, s13, 15
	s_cselect_b64 s[12:13], -1, 0
	v_writelane_b32 v253, s12, 16
	s_cmp_eq_u32 s14, 13
	s_nop 0
	v_writelane_b32 v253, s13, 17
	s_cselect_b64 s[12:13], -1, 0
	v_writelane_b32 v253, s12, 18
	s_cmp_eq_u32 s14, 12
	s_nop 0
	v_writelane_b32 v253, s13, 19
	s_cselect_b64 s[12:13], -1, 0
	v_writelane_b32 v253, s12, 20
	s_cmp_eq_u32 s14, 11
	s_nop 0
	v_writelane_b32 v253, s13, 21
	s_cselect_b64 s[12:13], -1, 0
	v_writelane_b32 v253, s12, 22
	s_cmp_eq_u32 s14, 10
	s_nop 0
	v_writelane_b32 v253, s13, 23
	s_cselect_b64 s[12:13], -1, 0
	v_writelane_b32 v253, s12, 24
	s_cmp_eq_u32 s14, 9
	s_nop 0
	v_writelane_b32 v253, s13, 25
	s_cselect_b64 s[12:13], -1, 0
	v_writelane_b32 v253, s12, 26
	s_cmp_eq_u32 s14, 8
	s_nop 0
	v_writelane_b32 v253, s13, 27
	s_cselect_b64 s[12:13], -1, 0
	v_writelane_b32 v253, s12, 28
	s_cmp_eq_u32 s14, 7
	s_nop 0
	v_writelane_b32 v253, s13, 29
	s_cselect_b64 s[12:13], -1, 0
	v_writelane_b32 v253, s12, 30
	s_cmp_eq_u32 s14, 6
	s_nop 0
	v_writelane_b32 v253, s13, 31
	s_cselect_b64 s[12:13], -1, 0
	v_writelane_b32 v253, s12, 32
	s_cmp_eq_u32 s14, 5
	s_nop 0
	v_writelane_b32 v253, s13, 33
	s_cselect_b64 s[12:13], -1, 0
	v_writelane_b32 v253, s12, 34
	s_cmp_eq_u32 s14, 4
	s_nop 0
	v_writelane_b32 v253, s13, 35
	s_cselect_b64 s[12:13], -1, 0
	v_writelane_b32 v253, s12, 36
	s_cmp_eq_u32 s14, 3
	s_nop 0
	v_writelane_b32 v253, s13, 37
	s_cselect_b64 s[12:13], -1, 0
	v_writelane_b32 v253, s12, 38
	s_cmp_eq_u32 s14, 2
	s_nop 0
	v_writelane_b32 v253, s13, 39
	s_cselect_b64 s[12:13], -1, 0
	v_writelane_b32 v253, s12, 40
	s_cmp_eq_u32 s14, 1
	s_nop 0
	v_writelane_b32 v253, s13, 41
	s_cselect_b64 s[12:13], -1, 0
	v_writelane_b32 v253, s12, 42
	s_cmp_eq_u32 s14, 0
	s_nop 0
	v_writelane_b32 v253, s13, 43
	s_cselect_b64 s[12:13], -1, 0
	v_writelane_b32 v253, s12, 44
	s_nop 1
	v_writelane_b32 v253, s13, 45
	s_lshl_b32 s12, s14, 8
	s_add_u32 s12, s8, s12
	s_addc_u32 s13, s9, 0
	s_add_u32 s26, s12, 0x1400
	s_addc_u32 s27, s13, 0
	v_writelane_b32 v253, s26, 46
	s_add_u32 s12, s12, 0x2400
	s_addc_u32 s13, s13, 0
	v_writelane_b32 v253, s27, 47
	v_writelane_b32 v253, s12, 48
	s_mov_b64 s[26:27], 0x400
	s_nop 0
	v_writelane_b32 v253, s13, 49
	s_add_u32 s12, s8, 0x3400
	s_addc_u32 s13, s9, 0
	v_writelane_b32 v253, s12, 50
	s_nop 1
	v_writelane_b32 v253, s13, 51
	s_add_u32 s12, s8, 0x3500
	s_addc_u32 s13, s9, 0
	v_writelane_b32 v253, s12, 52
	s_cmp_lt_i32 s22, 0
	s_nop 0
	v_writelane_b32 v253, s13, 53
	s_mul_i32 s12, s22, 33
	s_cselect_b32 s3, s12, s3
	s_add_i32 s3, s3, s21
	s_ashr_i32 s12, s3, 31
	s_lshr_b32 s12, s12, 27
	s_add_i32 s12, s3, s12
	s_and_b32 s13, s12, 0xffe0
	s_sub_i32 s3, s3, s13
	s_bfe_i32 s13, s3, 0x80000
	s_bfe_u32 s13, s13, 0x3000c
	s_add_i32 s13, s3, s13
	s_and_b32 s14, s13, 0xf8
	s_sub_i32 s3, s3, s14
	s_ashr_i32 s12, s12, 5
	s_lshl_b32 s12, s12, 3
	s_sext_i32_i8 s3, s3
	s_add_i32 s3, s12, s3
	v_writelane_b32 v253, s3, 54
	s_bfe_i32 s3, s13, 0x80000
	s_sext_i32_i16 s3, s3
	s_ashr_i32 s3, s3, 3
	v_writelane_b32 v253, s3, 55
	s_cmp_lt_i32 s22, 4
	s_mul_i32 s3, s22, 0x62
	s_cselect_b32 s3, s3, s17
	s_add_i32 s3, s3, s21
	s_mul_hi_i32 s12, s3, 0x2aaaaaab
	s_lshr_b32 s13, s12, 31
	s_ashr_i32 s12, s12, 4
	s_add_i32 s12, s12, s13
	s_mul_i32 s13, s12, 0x60
	s_lshl_b32 s12, s12, 3
	s_sub_i32 s13, s3, s13
	s_sub_i32 s3, 0x41, s12
	s_min_u32 s14, s3, 8
	v_cvt_f32_ubyte0_e32 v2, s14
	v_writelane_b32 v253, s22, 56
	v_cvt_f32_i32_e32 v1, s13
	v_rcp_iflag_f32_e32 v3, v2
	v_writelane_b32 v253, s21, 57
	s_bfe_i32 s3, s15, 0x10017
	v_writelane_b32 v253, s3, 58
	s_abs_i32 s3, s16
	v_writelane_b32 v253, s3, 59
	s_xor_b32 s3, s16, 0xffffff00
	s_max_i32 s3, s2, s3
	v_mul_f32_e32 v3, v1, v3
	v_writelane_b32 v253, s3, 60
	s_ashr_i32 s2, s2, 31
	v_trunc_f32_e32 v3, v3
	v_writelane_b32 v253, s2, 61
	s_ashr_i32 s2, s13, 30
	v_fma_f32 v1, -v3, v2, v1
	s_or_b32 s15, s2, 1
	v_cmp_ge_f32_e64 s[2:3], |v1|, v2
	s_and_b64 s[2:3], s[2:3], exec
	v_lshrrev_b32_e32 v1, 20, v0
	v_lshrrev_b32_e32 v0, 10, v0
	s_load_dword s3, s[0:1], 0xc8
	v_or_b32_e32 v0, v0, v1
	v_cvt_i32_f32_e32 v1, v3
	s_movk_i32 s2, 0x3ff
	v_and_or_b32 v0, v0, s2, v202
	s_mul_i32 s2, s19, s18
	s_waitcnt lgkmcnt(0)
	s_mul_i32 s49, s2, s3
	s_cselect_b32 s2, s15, 0
	v_readfirstlane_b32 s3, v1
	s_add_i32 s2, s3, s2
	s_mul_i32 s3, s2, s14
	s_sub_i32 s3, s13, s3
	s_sext_i32_i8 s3, s3
	s_add_i32 s3, s12, s3
	v_writelane_b32 v253, s3, 62
	s_sext_i32_i8 s2, s2
	v_writelane_b32 v253, s2, 63
	s_lshl_b32 s2, s18, 4
	v_writelane_b32 v254, s2, 0
	s_lshl_b32 s2, s93, 8
	s_ashr_i32 s97, s96, 31
	v_writelane_b32 v254, s2, 1
	s_lshl_b32 s2, s18, 8
	v_writelane_b32 v254, s2, 2
	s_lshl_b64 s[12:13], s[96:97], 12
	s_mul_i32 s2, s23, 0x744
	v_writelane_b32 v254, s12, 3
	s_add_u32 s2, s64, s2
	v_mov_b32_e32 v1, 0
	v_writelane_b32 v254, s13, 4
	v_writelane_b32 v254, s2, 5
	v_writelane_b32 v254, s23, 6
	v_writelane_b32 v254, s60, 7
	s_mul_hi_i32 s2, s23, 0x744
	s_addc_u32 s2, s65, s2
	v_writelane_b32 v254, s61, 8
	v_writelane_b32 v254, s62, 9
	v_writelane_b32 v254, s63, 10
	v_writelane_b32 v254, s64, 11
	v_writelane_b32 v254, s65, 12
	v_writelane_b32 v254, s66, 13
	v_writelane_b32 v254, s67, 14
	v_writelane_b32 v254, s68, 15
	v_writelane_b32 v254, s69, 16
	v_writelane_b32 v254, s70, 17
	v_writelane_b32 v254, s71, 18
	v_writelane_b32 v254, s72, 19
	v_writelane_b32 v254, s73, 20
	v_writelane_b32 v254, s74, 21
	v_writelane_b32 v254, s75, 22
	v_writelane_b32 v254, s2, 23
	s_mul_i32 s2, s18, 6
	s_add_i32 s2, s2, s20
	s_cmp_eq_u32 s18, 0x100
	s_cselect_b32 s3, 72, 0
	s_sub_i32 s2, s2, s3
	s_add_i32 s3, s2, 0xfffff9e8
	v_writelane_b32 v254, s3, 24
	s_addk_i32 s2, 0xfdc8
	v_writelane_b32 v254, s2, 25
	s_mul_i32 s2, s18, 24
	v_writelane_b32 v254, s2, 26
	s_add_i32 s2, s96, 0xffffe7a0
	s_cmp_eq_u32 s18, 0x100
	s_cselect_b32 s3, 0x120, 0
	s_sub_i32 s2, s2, s3
	v_writelane_b32 v254, s2, 27
	s_add_i32 s2, s56, 0xfffe7a00
	s_cmp_eq_u32 s18, 0x100
	s_cselect_b32 s3, 0x1200, 0
	s_sub_i32 s2, s2, s3
	v_writelane_b32 v254, s2, 28
	v_writelane_b32 v254, s20, 29
	s_add_i32 s2, s20, 0x3e0
	v_writelane_b32 v254, s2, 30
	s_lshl_b32 s2, s18, 7
	v_writelane_b32 v254, s2, 31
	s_add_i32 s2, 0, 0x820
	v_writelane_b32 v254, s2, 32
	s_add_i32 s2, 0, 0x5140
	v_writelane_b32 v254, s2, 33
	s_add_i32 s2, 0, 0x20800
	v_writelane_b32 v254, s2, 34
	s_add_i32 s2, 0, 0x201b0
	v_writelane_b32 v254, s2, 35
	s_add_i32 s2, 0, 0x21000
	v_writelane_b32 v254, s2, 36
	s_add_i32 s2, 0, 0x21004
	v_writelane_b32 v254, s2, 37
	s_mov_b32 s3, 0
	s_load_dwordx16 s[60:75], s[0:1], 0x0
	v_writelane_b32 v254, s2, 38
	s_mov_b32 s0, s96
	v_mbcnt_lo_u32_b32 v2, -1, 0
	v_writelane_b32 v254, s3, 39
	v_cmp_eq_u32_e64 s[2:3], 0, v0
	v_mbcnt_hi_u32_b32 v207, -1, v2
	v_and_b32_e32 v2, 64, v207
	v_writelane_b32 v254, s2, 40
	v_add_u32_e32 v208, 64, v2
	v_xor_b32_e32 v209, 32, v207
	v_writelane_b32 v254, s3, 41
	s_waitcnt lgkmcnt(0)
	v_writelane_b32 v254, s60, 42
	v_xor_b32_e32 v210, 16, v207
	v_xor_b32_e32 v211, 8, v207
	v_writelane_b32 v254, s61, 43
	v_writelane_b32 v254, s62, 44
	v_writelane_b32 v254, s63, 45
	v_writelane_b32 v254, s64, 46
	v_writelane_b32 v254, s65, 47
	v_writelane_b32 v254, s66, 48
	v_writelane_b32 v254, s67, 49
	v_writelane_b32 v254, s68, 50
	v_writelane_b32 v254, s69, 51
	v_writelane_b32 v254, s70, 52
	v_writelane_b32 v254, s71, 53
	v_writelane_b32 v254, s72, 54
	v_writelane_b32 v254, s73, 55
	v_writelane_b32 v254, s74, 56
	v_writelane_b32 v254, s75, 57
	v_writelane_b32 v254, s93, 58
	v_writelane_b32 v254, s84, 59
	v_xor_b32_e32 v212, 4, v207
	v_xor_b32_e32 v213, 2, v207
	v_writelane_b32 v255, s89, 0
	v_writelane_b32 v255, s90, 1
	v_writelane_b32 v255, s91, 2
	v_writelane_b32 v255, s0, 3
	v_writelane_b32 v254, s85, 60
	v_writelane_b32 v254, s86, 61
	v_writelane_b32 v255, s1, 4
	v_writelane_b32 v255, s46, 5
	v_writelane_b32 v254, s87, 62
	v_xor_b32_e32 v214, 1, v207
	v_writelane_b32 v255, s47, 6
	v_writelane_b32 v255, s48, 7
	v_writelane_b32 v255, s44, 8
	v_mov_b32_e32 v238, v1
	v_mov_b32_e32 v239, v1
	v_writelane_b32 v255, s45, 9
	v_writelane_b32 v255, s49, 10
	v_mov_b32_e32 v240, v1
	v_mov_b32_e32 v241, v1
	s_mov_b64 s[20:21], 0x80
	v_writelane_b32 v254, s88, 63
	v_writelane_b32 v255, s56, 11
	s_branch .LBB0_10

.LBB0_354:
	s_and_b64 vcc, exec, s[0:1]
	s_cbranch_vccnz .LBB0_482
	s_mov_b32 s98, 15
	v_ashrrev_i32_e32 v0, 31, v10
	v_lshrrev_b32_e32 v0, 26, v0
	v_add_u32_e32 v0, v10, v0
	v_ashrrev_i32_e32 v11, 6, v0
	v_bfe_i32 v0, v10, 27, 1
	v_lshlrev_b32_e32 v2, 4, v10
	v_lshrrev_b32_e32 v0, 22, v0
	v_add_u32_e32 v0, v2, v0
	v_and_b32_e32 v0, 0xfffffc00, v0
	v_sub_u32_e32 v0, v2, v0
	v_lshrrev_b32_e32 v3, 4, v0
	v_bitop3_b32 v3, v3, v0, 32 bitop3:0x6c
	v_ashrrev_i32_e32 v0, 31, v0
	v_lshrrev_b32_e32 v0, 26, v0
	v_add_u32_e32 v0, v3, v0
	v_ashrrev_i32_e32 v12, 6, v0
	v_mul_i32_i24_e32 v5, 64, v12
	v_sub_u32_e32 v3, v3, v5
	v_lshlrev_b32_e32 v4, 3, v11
	v_lshlrev_b32_e32 v0, 5, v11
	v_ashrrev_i16_sdwa v3, v206, sext(v3) dst_sel:DWORD dst_unused:UNUSED_PAD src0_sel:DWORD src1_sel:BYTE_0
	v_and_b32_e32 v4, 0x1ffff0, v4
	v_and_b32_e32 v0, 32, v0
	v_bfe_i32 v13, v3, 0, 16
	v_add_u32_e32 v0, v0, v13
	v_add_lshl_u32 v3, v12, v4, 11
	v_add_u32_e32 v2, 0x2000, v2
	v_lshl_add_u32 v0, v0, 1, v3
	v_ashrrev_i32_e32 v3, 31, v2
	v_lshrrev_b32_e32 v3, 22, v3
	s_mul_i32 s1, s62, 0x1880000
	v_add_u32_e32 v3, v2, v3
	s_mul_hi_i32 s0, s62, 0x1880000
	s_add_u32 s23, s46, s1
	v_ashrrev_i32_e32 v14, 10, v3
	s_addc_u32 s34, s47, s0
	s_ashr_i32 s2, s22, 6
	v_mul_i32_i24_e32 v3, 0x400, v14
	s_lshl_b32 s0, s42, 8
	v_sub_u32_e32 v2, v2, v3
	s_ashr_i32 s3, s22, 8
	s_lshl_b32 s35, s2, 10
	s_or_b32 s0, s0, 1
	v_lshrrev_b32_e32 v3, 4, v2
	s_cmp_lt_i32 s42, 64
	v_bitop3_b32 v2, v3, v2, 32 bitop3:0x6c
	s_cselect_b32 s0, s0, 0x4003
	v_ashrrev_i32_e32 v4, 31, v2
	s_ashr_i32 s1, s0, 31
	v_lshrrev_b32_e32 v4, 26, v4
	s_lshl_b64 s[0:1], s[0:1], 11
	v_readlane_b32 s12, v252, 20
	v_add_u32_e32 v4, v2, v4
	v_readlane_b32 s13, v252, 21
	s_add_u32 s0, s12, s0
	v_ashrrev_i32_e32 v15, 6, v4
	v_and_b32_e32 v4, 0xc0, v4
	s_addc_u32 s1, s13, s1
	s_ashr_i32 s15, s14, 31
	v_sub_u32_e32 v2, v2, v4
	s_lshl_b64 s[16:17], s[14:15], 19
	v_lshlrev_b32_e32 v3, 3, v14
	v_lshlrev_b32_e32 v5, 5, v14
	v_ashrrev_i16_sdwa v2, v206, sext(v2) dst_sel:DWORD dst_unused:UNUSED_PAD src0_sel:DWORD src1_sel:BYTE_0
	s_add_u32 s16, s23, s16
	v_and_b32_e32 v3, 0x1ffff0, v3
	v_and_b32_e32 v5, 32, v5
	v_bfe_i32 v16, v2, 0, 16
	s_addc_u32 s17, s34, s17
	s_add_i32 s54, s35, 0
	v_add_u32_e32 v2, v5, v16
	v_add_lshl_u32 v3, v15, v3, 11
	s_add_i32 m0, s54, 0x10000
	v_lshl_add_u32 v154, v2, 1, v3
	v_lshrrev_b32_e32 v5, 7, v202
	v_and_b32_e32 v4, 60, v202
	v_bfe_u32 v6, v202, 2, 4
	v_or_b32_e32 v4, v4, v5
	v_lshl_or_b32 v5, v5, 4, v6
	v_sub_u32_e32 v4, v4, v5
	v_lshlrev_b32_e32 v4, 11, v4
	v_add_u32_e32 v250, v0, v4
	v_add_u32_e32 v251, v154, v4
	global_load_lds_dwordx4 v0, s[16:17]
	s_add_i32 m0, s54, 0x12000
	s_add_i32 s55, s54, 0x2000
	global_load_lds_dwordx4 v154, s[16:17]
	s_mov_b32 m0, s54
	s_add_u32 s18, s16, 0x40000
	global_load_lds_dwordx4 v250, s[0:1]
	s_mov_b32 m0, s55
	s_addc_u32 s19, s17, 0
	global_load_lds_dwordx4 v251, s[0:1]
	s_add_i32 m0, s54, 0x14000
	v_writelane_b32 v255, s50, 17
	global_load_lds_dwordx4 v0, s[18:19]
	s_add_i32 m0, s54, 0x16000
	v_mov_b32_e32 v155, v1
	global_load_lds_dwordx4 v154, s[18:19]
	s_add_u32 s18, s0, 0x40000
	s_addc_u32 s19, s1, 0
	s_add_i32 s58, s54, 0x4000
	s_mov_b32 m0, s58
	s_add_i32 s59, s54, 0x6000
	global_load_lds_dwordx4 v250, s[18:19]
	s_mov_b32 m0, s59
	v_writelane_b32 v255, s51, 18
	global_load_lds_dwordx4 v251, s[18:19]
	v_lshl_add_u64 v[8:9], s[16:17], 0, v[0:1]
	v_lshl_add_u64 v[6:7], s[16:17], 0, v[154:155]
	v_lshl_add_u64 v[4:5], s[0:1], 0, v[0:1]
	s_cmp_lg_u32 s3, 1
	v_lshl_add_u64 v[2:3], s[0:1], 0, v[154:155]
	s_cbranch_scc1 .LBB0_357
	s_setprio 1
	s_barrier

.LBB0_358:
	s_cmp_eq_u32 s98, 15
	s_cbranch_scc1 .Lq_tail_done
	s_cmpk_gt_u32 s22, 0xff
	s_cbranch_scc0 .Lq_tail_done
	s_barrier
.Lq_tail_done:
	s_mov_b32 s98, s99
	v_readlane_b32 s46, v255, 5
	s_and_b64 vcc, exec, s[40:41]
	s_mov_b32 s14, s50
	s_mov_b32 s42, s18
	s_mov_b64 s[16:17], s[48:49]
	s_mov_b64 s[0:1], s[52:53]
	v_readlane_b32 s47, v255, 6
	v_readlane_b32 s48, v255, 7
	v_readlane_b32 s49, v255, 10
	s_cbranch_vccnz .LBB0_479
.LBB0_359:
	s_add_i32 s90, s90, 1
	v_readlane_b32 s2, v252, 27
	v_readlane_b32 s12, v252, 2
	s_mul_i32 s2, s90, s2
	s_mul_hi_u32 s3, s90, s12
	s_add_i32 s3, s3, s2
	s_mul_i32 s2, s90, s12
	v_readlane_b32 s12, v254, 58
	s_add_u32 s2, s2, s12
	v_readlane_b32 s12, v252, 26
	s_addc_u32 s3, s3, s12
	s_mov_b32 s99, 15
	v_readlane_b32 s12, v252, 2
	v_readlane_b32 s13, v254, 58
	s_cmp_eq_u32 s12, 0x100
	s_cbranch_scc0 .Lq_hdr_done
	s_cmp_eq_u32 s90, 3
	s_cbranch_scc0 .Lq_hdr_done
	s_lshr_b32 s2, s13, 2
	s_addk_i32 s2, 0x300
	s_and_b32 s12, s13, 3
	s_lshl_b32 s99, 1, s12
	s_cmp_lt_u32 s13, 48
	s_cselect_b32 s2, s2, 0x400
	s_mov_b32 s3, 0
.Lq_hdr_done:
	v_mov_b64_e32 v[2:3], 0x30b
	v_cmp_gt_i64_e64 s[40:41], s[2:3], v[2:3]
	s_and_b64 vcc, exec, s[40:41]
	v_readlane_b32 s13, v252, 3
	s_cbranch_vccnz .LBB0_365
	s_ashr_i32 s12, s2, 31
	s_lshr_b32 s12, s12, 29
	s_add_i32 s15, s2, s12
	s_and_b32 s12, s15, -8
	s_sub_i32 s43, s2, s12
	s_cmp_gt_i32 s43, 3
	s_mov_b64 s[18:19], -1
	s_cbranch_scc0 .LBB0_362
	s_mul_i32 s12, s43, 0x61
	s_add_i32 s44, s12, 4
	s_mov_b64 s[18:19], 0

.LBB0_365:
	v_mov_b64_e32 v[2:3], 0x30c
	v_cmp_lt_i64_e32 vcc, s[2:3], v[2:3]
	s_lshl_b32 s2, s18, 8
	s_or_b32 s2, s2, 1
	s_cmp_lt_i32 s18, 64
	s_cselect_b32 s2, s2, 0x4003
	s_ashr_i32 s3, s2, 31
	s_lshl_b64 s[2:3], s[2:3], 11
	v_readlane_b32 s12, v252, 20
	v_readlane_b32 s13, v252, 21
	s_add_u32 s52, s12, s2
	s_addc_u32 s53, s13, s3
	s_and_b64 s[2:3], vcc, exec
	s_cselect_b32 s15, s53, s1
	s_cselect_b32 s19, s52, s0
	s_ashr_i32 s51, s50, 31
	s_lshl_b64 s[2:3], s[50:51], 19
	s_add_u32 s48, s23, s2
	s_addc_u32 s49, s34, s3
	s_and_b64 s[2:3], vcc, exec
	s_cselect_b32 s43, s49, s17
	s_cselect_b32 s44, s48, s16
	s_add_u32 s0, s0, 0x40080
	s_addc_u32 s1, s1, 0
	s_add_u32 s45, s16, 0x100
	v_mov_b32_e32 v2, 0
	s_addc_u32 s46, s17, 0
	s_mov_b32 s47, -2
	v_mov_b32_e32 v3, v2
	v_mov_b32_e32 v4, v2
	v_mov_b32_e32 v5, v2
	v_mov_b32_e32 v6, v2
	v_mov_b32_e32 v7, v2
	v_mov_b32_e32 v8, v2
	v_mov_b32_e32 v9, v2
	v_mov_b32_e32 v10, v2
	v_mov_b32_e32 v11, v2
	v_mov_b32_e32 v12, v2
	v_mov_b32_e32 v13, v2
	v_mov_b32_e32 v14, v2
	v_mov_b32_e32 v15, v2
	v_mov_b32_e32 v16, v2
	v_mov_b32_e32 v17, v2
	v_mov_b32_e32 v18, v2
	v_mov_b32_e32 v19, v2
	v_mov_b32_e32 v20, v2
	v_mov_b32_e32 v21, v2
	v_mov_b32_e32 v22, v2
	v_mov_b32_e32 v23, v2
	v_mov_b32_e32 v24, v2
	v_mov_b32_e32 v25, v2
	v_mov_b32_e32 v26, v2
	v_mov_b32_e32 v27, v2
	v_mov_b32_e32 v28, v2
	v_mov_b32_e32 v29, v2
	v_mov_b32_e32 v30, v2
	v_mov_b32_e32 v31, v2
	v_mov_b32_e32 v32, v2
	v_mov_b32_e32 v33, v2
	v_mov_b32_e32 v66, v2
	v_mov_b32_e32 v67, v2
	v_mov_b32_e32 v68, v2
	v_mov_b32_e32 v69, v2
	v_mov_b32_e32 v70, v2
	v_mov_b32_e32 v71, v2
	v_mov_b32_e32 v72, v2
	v_mov_b32_e32 v73, v2
	v_mov_b32_e32 v74, v2
	v_mov_b32_e32 v75, v2
	v_mov_b32_e32 v76, v2
	v_mov_b32_e32 v77, v2
	v_mov_b32_e32 v78, v2
	v_mov_b32_e32 v79, v2
	v_mov_b32_e32 v80, v2
	v_mov_b32_e32 v81, v2
	v_mov_b32_e32 v82, v2
	v_mov_b32_e32 v83, v2
	v_mov_b32_e32 v84, v2
	v_mov_b32_e32 v85, v2
	v_mov_b32_e32 v86, v2
	v_mov_b32_e32 v87, v2
	v_mov_b32_e32 v88, v2
	v_mov_b32_e32 v89, v2
	v_mov_b32_e32 v90, v2
	v_mov_b32_e32 v91, v2
	v_mov_b32_e32 v92, v2
	v_mov_b32_e32 v93, v2
	v_mov_b32_e32 v94, v2
	v_mov_b32_e32 v95, v2
	v_mov_b32_e32 v96, v2
	v_mov_b32_e32 v97, v2
	v_mov_b32_e32 v34, v2
	v_mov_b32_e32 v35, v2
	v_mov_b32_e32 v36, v2
	v_mov_b32_e32 v37, v2
	v_mov_b32_e32 v38, v2
	v_mov_b32_e32 v39, v2
	v_mov_b32_e32 v40, v2
	v_mov_b32_e32 v41, v2
	v_mov_b32_e32 v42, v2
	v_mov_b32_e32 v43, v2
	v_mov_b32_e32 v44, v2
	v_mov_b32_e32 v45, v2
	v_mov_b32_e32 v46, v2
	v_mov_b32_e32 v47, v2
	v_mov_b32_e32 v48, v2
	v_mov_b32_e32 v49, v2
	v_mov_b32_e32 v50, v2
	v_mov_b32_e32 v51, v2
	v_mov_b32_e32 v52, v2
	v_mov_b32_e32 v53, v2
	v_mov_b32_e32 v54, v2
	v_mov_b32_e32 v55, v2
	v_mov_b32_e32 v56, v2
	v_mov_b32_e32 v57, v2
	v_mov_b32_e32 v58, v2
	v_mov_b32_e32 v59, v2
	v_mov_b32_e32 v60, v2
	v_mov_b32_e32 v61, v2
	v_mov_b32_e32 v62, v2
	v_mov_b32_e32 v63, v2
	v_mov_b32_e32 v64, v2
	v_mov_b32_e32 v65, v2
	v_mov_b32_e32 v98, v2
	v_mov_b32_e32 v99, v2
	v_mov_b32_e32 v100, v2
	v_mov_b32_e32 v101, v2
	v_mov_b32_e32 v102, v2
	v_mov_b32_e32 v103, v2
	v_mov_b32_e32 v104, v2
	v_mov_b32_e32 v105, v2
	v_mov_b32_e32 v106, v2
	v_mov_b32_e32 v107, v2
	v_mov_b32_e32 v108, v2
	v_mov_b32_e32 v109, v2
	v_mov_b32_e32 v110, v2
	v_mov_b32_e32 v111, v2
	v_mov_b32_e32 v112, v2
	v_mov_b32_e32 v113, v2
	v_mov_b32_e32 v114, v2
	v_mov_b32_e32 v115, v2
	v_mov_b32_e32 v116, v2
	v_mov_b32_e32 v117, v2
	v_mov_b32_e32 v118, v2
	v_mov_b32_e32 v119, v2
	v_mov_b32_e32 v120, v2
	v_mov_b32_e32 v121, v2
	v_mov_b32_e32 v122, v2
	v_mov_b32_e32 v123, v2
	v_mov_b32_e32 v124, v2
	v_mov_b32_e32 v125, v2
	v_mov_b32_e32 v126, v2
	v_mov_b32_e32 v127, v2
	v_mov_b32_e32 v128, v2
	v_mov_b32_e32 v129, v2
	s_cmp_lg_u32 s98, 15
	s_cbranch_scc1 .Lq_unit

.Lq_epi:
	s_lshl_b32 s2, s42, 8
	s_add_i32 s2, s2, s92
	s_lshl_b32 s3, s14, 8
	s_or_b32 s3, s3, s93
	v_readlane_b32 s44, v255, 8
	v_readlane_b32 s45, v255, 9
	s_add_u32 s60, s8, 0xc404000
	s_addc_u32 s61, s9, 0
	v_lshl_add_u32 v166, v226, 2, s2
	s_cmp_lt_i32 s42, 64
	s_cselect_b32 s47, 1, 0
	v_mul_lo_u32 v167, v166, s57
	s_nop 0
	v_lshl_add_u32 v167, v228, 1, v167
	s_and_b32 s12, s98, 5
	s_cbranch_scc0 .Lip0_end
	s_cmpk_gt_i32 s3, 0xb7f
	s_cbranch_scc1 .Lip0_end
	s_lshl_b32 s12, s3, 1
	v_add_u32_e32 v169, s12, v167
	s_add_i32 s0, s3, 0xfffffc00
	s_add_i32 s1, s3, 0xfffff780
	s_min_u32 s12, s0, s1
	s_cmpk_lt_u32 s12, 0x180
	s_cbranch_scc1 .Lip0_V
	s_add_i32 s12, s3, 0xfffffa80
	s_cmpk_lt_u32 s12, 0x300
	s_cbranch_scc1 .Lip0_R
	s_add_i32 s12, s3, 0xffffff00
	s_cmpk_lt_u32 s12, 0x180
	s_cbranch_scc0 .Lip0_nonq
	v_mul_f32_e32 v126, 0x3e38aa3b, v126
	v_mul_f32_e32 v127, 0x3e38aa3b, v127
	v_mul_f32_e32 v128, 0x3e38aa3b, v128
	v_mul_f32_e32 v129, 0x3e38aa3b, v129
	v_mul_f32_e32 v122, 0x3e38aa3b, v122
	v_mul_f32_e32 v123, 0x3e38aa3b, v123
	v_mul_f32_e32 v124, 0x3e38aa3b, v124
	v_mul_f32_e32 v125, 0x3e38aa3b, v125
	v_mul_f32_e32 v118, 0x3e38aa3b, v118
	v_mul_f32_e32 v119, 0x3e38aa3b, v119
	v_mul_f32_e32 v120, 0x3e38aa3b, v120
	v_mul_f32_e32 v121, 0x3e38aa3b, v121
	v_mul_f32_e32 v114, 0x3e38aa3b, v114
	v_mul_f32_e32 v115, 0x3e38aa3b, v115
	v_mul_f32_e32 v116, 0x3e38aa3b, v116
	v_mul_f32_e32 v117, 0x3e38aa3b, v117
	v_mul_f32_e32 v110, 0x3e38aa3b, v110
	v_mul_f32_e32 v111, 0x3e38aa3b, v111
	v_mul_f32_e32 v112, 0x3e38aa3b, v112
	v_mul_f32_e32 v113, 0x3e38aa3b, v113
	v_mul_f32_e32 v106, 0x3e38aa3b, v106
	v_mul_f32_e32 v107, 0x3e38aa3b, v107
	v_mul_f32_e32 v108, 0x3e38aa3b, v108
	v_mul_f32_e32 v109, 0x3e38aa3b, v109
	v_mul_f32_e32 v102, 0x3e38aa3b, v102
	v_mul_f32_e32 v103, 0x3e38aa3b, v103
	v_mul_f32_e32 v104, 0x3e38aa3b, v104
	v_mul_f32_e32 v105, 0x3e38aa3b, v105
	v_mul_f32_e32 v98, 0x3e38aa3b, v98
	v_mul_f32_e32 v99, 0x3e38aa3b, v99
	v_mul_f32_e32 v100, 0x3e38aa3b, v100
	v_mul_f32_e32 v101, 0x3e38aa3b, v101
	v_mul_f32_e32 v94, 0x3e38aa3b, v94
	v_mul_f32_e32 v95, 0x3e38aa3b, v95
	v_mul_f32_e32 v96, 0x3e38aa3b, v96
	v_mul_f32_e32 v97, 0x3e38aa3b, v97
	v_mul_f32_e32 v90, 0x3e38aa3b, v90
	v_mul_f32_e32 v91, 0x3e38aa3b, v91
	v_mul_f32_e32 v92, 0x3e38aa3b, v92
	v_mul_f32_e32 v93, 0x3e38aa3b, v93
	v_mul_f32_e32 v86, 0x3e38aa3b, v86
	v_mul_f32_e32 v87, 0x3e38aa3b, v87
	v_mul_f32_e32 v88, 0x3e38aa3b, v88
	v_mul_f32_e32 v89, 0x3e38aa3b, v89
	v_mul_f32_e32 v82, 0x3e38aa3b, v82
	v_mul_f32_e32 v83, 0x3e38aa3b, v83
	v_mul_f32_e32 v84, 0x3e38aa3b, v84
	v_mul_f32_e32 v85, 0x3e38aa3b, v85
	v_mul_f32_e32 v78, 0x3e38aa3b, v78
	v_mul_f32_e32 v79, 0x3e38aa3b, v79
	v_mul_f32_e32 v80, 0x3e38aa3b, v80
	v_mul_f32_e32 v81, 0x3e38aa3b, v81
	v_mul_f32_e32 v74, 0x3e38aa3b, v74
	v_mul_f32_e32 v75, 0x3e38aa3b, v75
	v_mul_f32_e32 v76, 0x3e38aa3b, v76
	v_mul_f32_e32 v77, 0x3e38aa3b, v77
	v_mul_f32_e32 v70, 0x3e38aa3b, v70
	v_mul_f32_e32 v71, 0x3e38aa3b, v71
	v_mul_f32_e32 v72, 0x3e38aa3b, v72
	v_mul_f32_e32 v73, 0x3e38aa3b, v73
	v_mul_f32_e32 v66, 0x3e38aa3b, v66
	v_mul_f32_e32 v67, 0x3e38aa3b, v67
	v_mul_f32_e32 v68, 0x3e38aa3b, v68
	v_mul_f32_e32 v69, 0x3e38aa3b, v69

.Lip0_nogate:
	s_bitcmp1_b32 s98, 0
	s_cbranch_scc0 .Lip0_ps0
	v_cvt_pk_bf16_f32 v138, v126, v127
	v_cvt_pk_bf16_f32 v139, v128, v129
	global_store_dwordx2 v169, v[138:139], s[60:61]
	v_cvt_pk_bf16_f32 v140, v122, v123
	v_cvt_pk_bf16_f32 v141, v124, v125
	global_store_dwordx2 v169, v[140:141], s[60:61] offset:32
	v_add_u32_e32 v170, 0x1700, v169
	v_cvt_pk_bf16_f32 v142, v118, v119
	v_cvt_pk_bf16_f32 v143, v120, v121
	global_store_dwordx2 v170, v[142:143], s[60:61]
	v_cvt_pk_bf16_f32 v144, v114, v115
	v_cvt_pk_bf16_f32 v145, v116, v117
	global_store_dwordx2 v170, v[144:145], s[60:61] offset:32
	v_add_u32_e32 v171, 0x2e00, v169
	v_cvt_pk_bf16_f32 v146, v110, v111
	v_cvt_pk_bf16_f32 v147, v112, v113
	global_store_dwordx2 v171, v[146:147], s[60:61]
	v_cvt_pk_bf16_f32 v148, v106, v107
	v_cvt_pk_bf16_f32 v149, v108, v109
	global_store_dwordx2 v171, v[148:149], s[60:61] offset:32
	v_add_u32_e32 v172, 0x4500, v169
	v_cvt_pk_bf16_f32 v150, v102, v103
	v_cvt_pk_bf16_f32 v151, v104, v105
	global_store_dwordx2 v172, v[150:151], s[60:61]
	v_cvt_pk_bf16_f32 v152, v98, v99
	v_cvt_pk_bf16_f32 v153, v100, v101
	global_store_dwordx2 v172, v[152:153], s[60:61] offset:32
.Lip0_ps0:
	s_bitcmp1_b32 s98, 2
	s_cbranch_scc0 .Lip0_ps1
	v_add_u32_e32 v173, 0xb8000, v169
	v_cvt_pk_bf16_f32 v138, v94, v95
	v_cvt_pk_bf16_f32 v139, v96, v97
	global_store_dwordx2 v173, v[138:139], s[60:61]
	v_cvt_pk_bf16_f32 v140, v90, v91
	v_cvt_pk_bf16_f32 v141, v92, v93
	global_store_dwordx2 v173, v[140:141], s[60:61] offset:32
	v_add_u32_e32 v174, 0xb9700, v169
	v_cvt_pk_bf16_f32 v142, v86, v87
	v_cvt_pk_bf16_f32 v143, v88, v89
	global_store_dwordx2 v174, v[142:143], s[60:61]
	v_cvt_pk_bf16_f32 v144, v82, v83
	v_cvt_pk_bf16_f32 v145, v84, v85
	global_store_dwordx2 v174, v[144:145], s[60:61] offset:32
	v_add_u32_e32 v175, 0xbae00, v169
	v_cvt_pk_bf16_f32 v146, v78, v79
	v_cvt_pk_bf16_f32 v147, v80, v81
	global_store_dwordx2 v175, v[146:147], s[60:61]
	v_cvt_pk_bf16_f32 v148, v74, v75
	v_cvt_pk_bf16_f32 v149, v76, v77
	global_store_dwordx2 v175, v[148:149], s[60:61] offset:32
	v_add_u32_e32 v176, 0xbc500, v169
	v_cvt_pk_bf16_f32 v150, v70, v71
	v_cvt_pk_bf16_f32 v151, v72, v73
	global_store_dwordx2 v176, v[150:151], s[60:61]
	v_cvt_pk_bf16_f32 v152, v66, v67
	v_cvt_pk_bf16_f32 v153, v68, v69
	global_store_dwordx2 v176, v[152:153], s[60:61] offset:32

.Lip0_V:
	s_cmpk_lt_u32 s0, 0x180
	s_cbranch_scc0 .Lip0_RV
	s_lshr_b32 s12, s0, 6
	s_mul_i32 s12, s12, 0x208000
	s_and_b32 s15, s0, 63
	s_lshl_b32 s15, s15, 7
	s_add_u32 s12, s12, s15
	s_lshl_b32 s15, s2, 7
	s_add_u32 s12, s12, s15
	s_add_u32 s12, s12, 0x12174000
	s_add_u32 s64, s8, s12
	s_addc_u32 s65, s9, 0
	v_lshlrev_b32_e32 v168, 7, v228
	v_lshl_add_u32 v168, v226, 3, v168
	v_add_u32_e32 v170, 0x4000, v168
	s_bitcmp1_b32 s98, 0
	s_cbranch_scc0 .Lip0_nv0
	v_cvt_pk_bf16_f32 v138, v126, v118
	v_cvt_pk_bf16_f32 v139, v110, v102
	global_store_dwordx2 v168, v[138:139], s[64:65]
	v_cvt_pk_bf16_f32 v140, v127, v119
	v_cvt_pk_bf16_f32 v141, v111, v103
	global_store_dwordx2 v168, v[140:141], s[64:65] offset:128
	v_cvt_pk_bf16_f32 v142, v128, v120
	v_cvt_pk_bf16_f32 v143, v112, v104
	global_store_dwordx2 v168, v[142:143], s[64:65] offset:256
	v_cvt_pk_bf16_f32 v144, v129, v121
	v_cvt_pk_bf16_f32 v145, v113, v105
	global_store_dwordx2 v168, v[144:145], s[64:65] offset:384
	v_cvt_pk_bf16_f32 v146, v122, v114
	v_cvt_pk_bf16_f32 v147, v106, v98
	global_store_dwordx2 v168, v[146:147], s[64:65] offset:2048
	v_cvt_pk_bf16_f32 v148, v123, v115
	v_cvt_pk_bf16_f32 v149, v107, v99
	global_store_dwordx2 v168, v[148:149], s[64:65] offset:2176
	v_cvt_pk_bf16_f32 v150, v124, v116
	v_cvt_pk_bf16_f32 v151, v108, v100
	global_store_dwordx2 v168, v[150:151], s[64:65] offset:2304
	v_cvt_pk_bf16_f32 v152, v125, v117
	v_cvt_pk_bf16_f32 v153, v109, v101
	global_store_dwordx2 v168, v[152:153], s[64:65] offset:2432
.Lip0_nv0:
	s_bitcmp1_b32 s98, 2
	s_cbranch_scc0 .Lip0_nv1
	v_cvt_pk_bf16_f32 v138, v94, v86
	v_cvt_pk_bf16_f32 v139, v78, v70
	global_store_dwordx2 v170, v[138:139], s[64:65]
	v_cvt_pk_bf16_f32 v140, v95, v87
	v_cvt_pk_bf16_f32 v141, v79, v71
	global_store_dwordx2 v170, v[140:141], s[64:65] offset:128
	v_cvt_pk_bf16_f32 v142, v96, v88
	v_cvt_pk_bf16_f32 v143, v80, v72
	global_store_dwordx2 v170, v[142:143], s[64:65] offset:256
	v_cvt_pk_bf16_f32 v144, v97, v89
	v_cvt_pk_bf16_f32 v145, v81, v73
	global_store_dwordx2 v170, v[144:145], s[64:65] offset:384
	v_cvt_pk_bf16_f32 v146, v90, v82
	v_cvt_pk_bf16_f32 v147, v74, v66
	global_store_dwordx2 v170, v[146:147], s[64:65] offset:2048
	v_cvt_pk_bf16_f32 v148, v91, v83
	v_cvt_pk_bf16_f32 v149, v75, v67
	global_store_dwordx2 v170, v[148:149], s[64:65] offset:2176
	v_cvt_pk_bf16_f32 v150, v92, v84
	v_cvt_pk_bf16_f32 v151, v76, v68
	global_store_dwordx2 v170, v[150:151], s[64:65] offset:2304
	v_cvt_pk_bf16_f32 v152, v93, v85
	v_cvt_pk_bf16_f32 v153, v77, v69
	global_store_dwordx2 v170, v[152:153], s[64:65] offset:2432

.Lip0_RV:
	s_cmpk_lt_u32 s0, 0x180
	s_cselect_b32 s12, s0, s1
	s_mov_b32 s15, 0x12da4000
	s_cselect_b32 s15, 0x12174000, s15
	s_add_u32 s64, s8, s15
	s_addc_u32 s65, s9, 0
	v_add_u32_e32 v168, s12, v228
	v_mul_u32_u24_e32 v168, 0x8200, v168
	v_lshl_add_u32 v168, v166, 1, v168
	s_bitcmp1_b32 s98, 0
	s_cbranch_scc0 .Lip0_rv0
	v_cvt_pk_bf16_f32 v138, v126, v118
	v_cvt_pk_bf16_f32 v139, v110, v102
	global_store_dwordx2 v168, v[138:139], s[64:65]
	v_add_u32_e32 v170, 0x8200, v168
	v_cvt_pk_bf16_f32 v140, v127, v119
	v_cvt_pk_bf16_f32 v141, v111, v103
	global_store_dwordx2 v170, v[140:141], s[64:65]
	v_add_u32_e32 v171, 0x10400, v168
	v_cvt_pk_bf16_f32 v142, v128, v120
	v_cvt_pk_bf16_f32 v143, v112, v104
	global_store_dwordx2 v171, v[142:143], s[64:65]
	v_add_u32_e32 v172, 0x18600, v168
	v_cvt_pk_bf16_f32 v144, v129, v121
	v_cvt_pk_bf16_f32 v145, v113, v105
	global_store_dwordx2 v172, v[144:145], s[64:65]
	v_add_u32_e32 v173, 0x82000, v168
	v_cvt_pk_bf16_f32 v146, v122, v114
	v_cvt_pk_bf16_f32 v147, v106, v98
	global_store_dwordx2 v173, v[146:147], s[64:65]
	v_add_u32_e32 v174, 0x8a200, v168
	v_cvt_pk_bf16_f32 v148, v123, v115
	v_cvt_pk_bf16_f32 v149, v107, v99
	global_store_dwordx2 v174, v[148:149], s[64:65]
	v_add_u32_e32 v175, 0x92400, v168
	v_cvt_pk_bf16_f32 v150, v124, v116
	v_cvt_pk_bf16_f32 v151, v108, v100
	global_store_dwordx2 v175, v[150:151], s[64:65]
	v_add_u32_e32 v176, 0x9a600, v168
	v_cvt_pk_bf16_f32 v152, v125, v117
	v_cvt_pk_bf16_f32 v153, v109, v101
	global_store_dwordx2 v176, v[152:153], s[64:65]
.Lip0_rv0:
	s_bitcmp1_b32 s98, 2
	s_cbranch_scc0 .Lip0_rv1
	v_cvt_pk_bf16_f32 v138, v94, v86
	v_cvt_pk_bf16_f32 v139, v78, v70
	global_store_dwordx2 v168, v[138:139], s[64:65] offset:256
	v_add_u32_e32 v177, 0x8200, v168
	v_cvt_pk_bf16_f32 v140, v95, v87
	v_cvt_pk_bf16_f32 v141, v79, v71
	global_store_dwordx2 v177, v[140:141], s[64:65] offset:256
	v_add_u32_e32 v170, 0x10400, v168
	v_cvt_pk_bf16_f32 v142, v96, v88
	v_cvt_pk_bf16_f32 v143, v80, v72
	global_store_dwordx2 v170, v[142:143], s[64:65] offset:256
	v_add_u32_e32 v171, 0x18600, v168
	v_cvt_pk_bf16_f32 v144, v97, v89
	v_cvt_pk_bf16_f32 v145, v81, v73
	global_store_dwordx2 v171, v[144:145], s[64:65] offset:256
	v_add_u32_e32 v172, 0x82000, v168
	v_cvt_pk_bf16_f32 v146, v90, v82
	v_cvt_pk_bf16_f32 v147, v74, v66
	global_store_dwordx2 v172, v[146:147], s[64:65] offset:256
	v_add_u32_e32 v173, 0x8a200, v168
	v_cvt_pk_bf16_f32 v148, v91, v83
	v_cvt_pk_bf16_f32 v149, v75, v67
	global_store_dwordx2 v173, v[148:149], s[64:65] offset:256
	v_add_u32_e32 v174, 0x92400, v168
	v_cvt_pk_bf16_f32 v150, v92, v84
	v_cvt_pk_bf16_f32 v151, v76, v68
	global_store_dwordx2 v174, v[150:151], s[64:65] offset:256
	v_add_u32_e32 v175, 0x9a600, v168
	v_cvt_pk_bf16_f32 v152, v93, v85
	v_cvt_pk_bf16_f32 v153, v77, v69
	global_store_dwordx2 v175, v[152:153], s[64:65] offset:256
.Lip0_rv1:
	s_branch .Lip0_end
.Lip0_R:
	s_cmpk_gt_i32 s3, 0x6ff
	s_cselect_b32 s46, 1, 0
	v_lshlrev_b32_e32 v130, 8, v226
	v_lshl_add_u32 v130, v228, 2, v130
	v_lshl_add_u32 v131, v228, 2, s2
	s_bitcmp1_b32 s3, 5
	s_cselect_b32 s12, 64, 0
	s_cselect_b32 s15, 0, 0x80
	s_cselect_b64 vcc, -1, 0
	s_add_u32 s16, s44, 0x4000
	s_addc_u32 s17, s45, 0
	v_cndmask_b32_e32 v130, v131, v130, vcc
	v_add_u32_e32 v131, s12, v130
	v_add_u32_e32 v132, s12, v131
	v_add_u32_e32 v133, s12, v132
	s_cmp_lg_u32 s47, 0
	s_cbranch_scc0 .Lip0_Rnoload
	global_load_dwordx4 v[170:173], v130, s[44:45]
	global_load_dwordx4 v[186:189], v130, s[16:17]
	global_load_dwordx4 v[174:177], v131, s[44:45]
	global_load_dwordx4 v[190:193], v131, s[16:17]
	global_load_dwordx4 v[178:181], v132, s[44:45]
	global_load_dwordx4 v[194:197], v132, s[16:17]
	global_load_dwordx4 v[182:185], v133, s[44:45]
	global_load_dwordx4 v[198:201], v133, s[16:17]

.Lip0_a0_noscale:
	s_bitcmp1_b32 s98, 0
	s_cbranch_scc0 .Lip0_a0_nokt
	v_cvt_pk_bf16_f32 v146, v126, v127
	v_cvt_pk_bf16_f32 v147, v128, v129
	global_store_dwordx2 v169, v[146:147], s[60:61]
	v_cvt_pk_bf16_f32 v148, v122, v123
	v_cvt_pk_bf16_f32 v149, v124, v125
	global_store_dwordx2 v169, v[148:149], s[60:61] offset:32
	v_add_u32_e32 v234, 0x1700, v169
	v_cvt_pk_bf16_f32 v150, v118, v119
	v_cvt_pk_bf16_f32 v151, v120, v121
	global_store_dwordx2 v234, v[150:151], s[60:61]
	v_cvt_pk_bf16_f32 v152, v114, v115
	v_cvt_pk_bf16_f32 v153, v116, v117
	global_store_dwordx2 v234, v[152:153], s[60:61] offset:32
	v_add_u32_e32 v235, 0x2e00, v169
	v_cvt_pk_bf16_f32 v146, v110, v111
	v_cvt_pk_bf16_f32 v147, v112, v113
	global_store_dwordx2 v235, v[146:147], s[60:61]
	v_cvt_pk_bf16_f32 v148, v106, v107
	v_cvt_pk_bf16_f32 v149, v108, v109
	global_store_dwordx2 v235, v[148:149], s[60:61] offset:32
	v_add_u32_e32 v236, 0x4500, v169
	v_cvt_pk_bf16_f32 v150, v102, v103
	v_cvt_pk_bf16_f32 v151, v104, v105
	global_store_dwordx2 v236, v[150:151], s[60:61]
	v_cvt_pk_bf16_f32 v152, v98, v99
	v_cvt_pk_bf16_f32 v153, v100, v101
	global_store_dwordx2 v236, v[152:153], s[60:61] offset:32
	s_cmp_lg_u32 s46, 0
	s_cbranch_scc0 .Lip0_a0_nokt
	v_mul_f32_e32 v142, v126, v134
	v_mul_f32_e32 v143, v118, v135
	v_mul_f32_e32 v144, v110, v136
	v_mul_f32_e32 v145, v102, v137
	v_cvt_pk_bf16_f32 v146, v142, v143
	v_cvt_pk_bf16_f32 v147, v144, v145
	global_store_dwordx2 v168, v[146:147], s[24:25]
	v_add_u32_e32 v237, 0x8200, v168
	v_mul_f32_e32 v142, v127, v134
	v_mul_f32_e32 v143, v119, v135
	v_mul_f32_e32 v144, v111, v136
	v_mul_f32_e32 v145, v103, v137
	v_cvt_pk_bf16_f32 v148, v142, v143
	v_cvt_pk_bf16_f32 v149, v144, v145
	global_store_dwordx2 v237, v[148:149], s[24:25]
	v_add_u32_e32 v242, 0x10400, v168
	v_mul_f32_e32 v142, v128, v134
	v_mul_f32_e32 v143, v120, v135
	v_mul_f32_e32 v144, v112, v136
	v_mul_f32_e32 v145, v104, v137
	v_cvt_pk_bf16_f32 v150, v142, v143
	v_cvt_pk_bf16_f32 v151, v144, v145
	global_store_dwordx2 v242, v[150:151], s[24:25]
	v_add_u32_e32 v243, 0x18600, v168
	v_mul_f32_e32 v142, v129, v134
	v_mul_f32_e32 v143, v121, v135
	v_mul_f32_e32 v144, v113, v136
	v_mul_f32_e32 v145, v105, v137
	v_cvt_pk_bf16_f32 v152, v142, v143
	v_cvt_pk_bf16_f32 v153, v144, v145
	global_store_dwordx2 v243, v[152:153], s[24:25]
	v_add_u32_e32 v244, 0x82000, v168
	v_mul_f32_e32 v142, v122, v134
	v_mul_f32_e32 v143, v114, v135
	v_mul_f32_e32 v144, v106, v136
	v_mul_f32_e32 v145, v98, v137
	v_cvt_pk_bf16_f32 v146, v142, v143
	v_cvt_pk_bf16_f32 v147, v144, v145
	global_store_dwordx2 v244, v[146:147], s[24:25]
	v_add_u32_e32 v245, 0x8a200, v168
	v_mul_f32_e32 v142, v123, v134
	v_mul_f32_e32 v143, v115, v135
	v_mul_f32_e32 v144, v107, v136
	v_mul_f32_e32 v145, v99, v137
	v_cvt_pk_bf16_f32 v148, v142, v143
	v_cvt_pk_bf16_f32 v149, v144, v145
	global_store_dwordx2 v245, v[148:149], s[24:25]
	v_add_u32_e32 v234, 0x92400, v168
	v_mul_f32_e32 v142, v124, v134
	v_mul_f32_e32 v143, v116, v135
	v_mul_f32_e32 v144, v108, v136
	v_mul_f32_e32 v145, v100, v137
	v_cvt_pk_bf16_f32 v150, v142, v143
	v_cvt_pk_bf16_f32 v151, v144, v145
	global_store_dwordx2 v234, v[150:151], s[24:25]
	v_add_u32_e32 v235, 0x9a600, v168
	v_mul_f32_e32 v142, v125, v134
	v_mul_f32_e32 v143, v117, v135
	v_mul_f32_e32 v144, v109, v136
	v_mul_f32_e32 v145, v101, v137
	v_cvt_pk_bf16_f32 v152, v142, v143
	v_cvt_pk_bf16_f32 v153, v144, v145
	global_store_dwordx2 v235, v[152:153], s[24:25]
	v_mul_f32_e32 v142, v126, v138
	v_mul_f32_e32 v143, v118, v139
	v_mul_f32_e32 v144, v110, v140
	v_mul_f32_e32 v145, v102, v141
	v_cvt_pk_bf16_f32 v146, v142, v143
	v_cvt_pk_bf16_f32 v147, v144, v145
	global_store_dwordx2 v168, v[146:147], s[82:83]
	v_add_u32_e32 v236, 0x8200, v168
	v_mul_f32_e32 v142, v127, v138
	v_mul_f32_e32 v143, v119, v139
	v_mul_f32_e32 v144, v111, v140
	v_mul_f32_e32 v145, v103, v141
	v_cvt_pk_bf16_f32 v148, v142, v143
	v_cvt_pk_bf16_f32 v149, v144, v145
	global_store_dwordx2 v236, v[148:149], s[82:83]
	v_add_u32_e32 v237, 0x10400, v168
	v_mul_f32_e32 v142, v128, v138
	v_mul_f32_e32 v143, v120, v139
	v_mul_f32_e32 v144, v112, v140
	v_mul_f32_e32 v145, v104, v141
	v_cvt_pk_bf16_f32 v150, v142, v143
	v_cvt_pk_bf16_f32 v151, v144, v145
	global_store_dwordx2 v237, v[150:151], s[82:83]
	v_add_u32_e32 v242, 0x18600, v168
	v_mul_f32_e32 v142, v129, v138
	v_mul_f32_e32 v143, v121, v139
	v_mul_f32_e32 v144, v113, v140
	v_mul_f32_e32 v145, v105, v141
	v_cvt_pk_bf16_f32 v152, v142, v143
	v_cvt_pk_bf16_f32 v153, v144, v145
	global_store_dwordx2 v242, v[152:153], s[82:83]
	v_add_u32_e32 v243, 0x82000, v168
	v_mul_f32_e32 v142, v122, v138
	v_mul_f32_e32 v143, v114, v139
	v_mul_f32_e32 v144, v106, v140
	v_mul_f32_e32 v145, v98, v141
	v_cvt_pk_bf16_f32 v146, v142, v143
	v_cvt_pk_bf16_f32 v147, v144, v145
	global_store_dwordx2 v243, v[146:147], s[82:83]
	v_add_u32_e32 v244, 0x8a200, v168
	v_mul_f32_e32 v142, v123, v138
	v_mul_f32_e32 v143, v115, v139
	v_mul_f32_e32 v144, v107, v140
	v_mul_f32_e32 v145, v99, v141
	v_cvt_pk_bf16_f32 v148, v142, v143
	v_cvt_pk_bf16_f32 v149, v144, v145
	global_store_dwordx2 v244, v[148:149], s[82:83]
	v_add_u32_e32 v245, 0x92400, v168
	v_mul_f32_e32 v142, v124, v138
	v_mul_f32_e32 v143, v116, v139
	v_mul_f32_e32 v144, v108, v140
	v_mul_f32_e32 v145, v100, v141
	v_cvt_pk_bf16_f32 v150, v142, v143
	v_cvt_pk_bf16_f32 v151, v144, v145
	global_store_dwordx2 v245, v[150:151], s[82:83]
	v_add_u32_e32 v234, 0x9a600, v168
	v_mul_f32_e32 v142, v125, v138
	v_mul_f32_e32 v143, v117, v139
	v_mul_f32_e32 v144, v109, v140
	v_mul_f32_e32 v145, v101, v141
	v_cvt_pk_bf16_f32 v152, v142, v143
	v_cvt_pk_bf16_f32 v153, v144, v145
	global_store_dwordx2 v234, v[152:153], s[82:83]

.Lip0_a1_noscale:
	s_bitcmp1_b32 s98, 2
	s_cbranch_scc0 .Lip0_a1_nokt
	v_add_u32_e32 v234, 0xb8000, v169
	v_cvt_pk_bf16_f32 v146, v94, v95
	v_cvt_pk_bf16_f32 v147, v96, v97
	global_store_dwordx2 v234, v[146:147], s[60:61]
	v_cvt_pk_bf16_f32 v148, v90, v91
	v_cvt_pk_bf16_f32 v149, v92, v93
	global_store_dwordx2 v234, v[148:149], s[60:61] offset:32
	v_add_u32_e32 v235, 0xb9700, v169
	v_cvt_pk_bf16_f32 v150, v86, v87
	v_cvt_pk_bf16_f32 v151, v88, v89
	global_store_dwordx2 v235, v[150:151], s[60:61]
	v_cvt_pk_bf16_f32 v152, v82, v83
	v_cvt_pk_bf16_f32 v153, v84, v85
	global_store_dwordx2 v235, v[152:153], s[60:61] offset:32
	v_add_u32_e32 v236, 0xbae00, v169
	v_cvt_pk_bf16_f32 v146, v78, v79
	v_cvt_pk_bf16_f32 v147, v80, v81
	global_store_dwordx2 v236, v[146:147], s[60:61]
	v_cvt_pk_bf16_f32 v148, v74, v75
	v_cvt_pk_bf16_f32 v149, v76, v77
	global_store_dwordx2 v236, v[148:149], s[60:61] offset:32
	v_add_u32_e32 v237, 0xbc500, v169
	v_cvt_pk_bf16_f32 v150, v70, v71
	v_cvt_pk_bf16_f32 v151, v72, v73
	global_store_dwordx2 v237, v[150:151], s[60:61]
	v_cvt_pk_bf16_f32 v152, v66, v67
	v_cvt_pk_bf16_f32 v153, v68, v69
	global_store_dwordx2 v237, v[152:153], s[60:61] offset:32
	s_cmp_lg_u32 s46, 0
	s_cbranch_scc0 .Lip0_a1_nokt
	v_mul_f32_e32 v142, v94, v134
	v_mul_f32_e32 v143, v86, v135
	v_mul_f32_e32 v144, v78, v136
	v_mul_f32_e32 v145, v70, v137
	v_cvt_pk_bf16_f32 v146, v142, v143
	v_cvt_pk_bf16_f32 v147, v144, v145
	global_store_dwordx2 v168, v[146:147], s[24:25] offset:256
	v_add_u32_e32 v242, 0x8200, v168
	v_mul_f32_e32 v142, v95, v134
	v_mul_f32_e32 v143, v87, v135
	v_mul_f32_e32 v144, v79, v136
	v_mul_f32_e32 v145, v71, v137
	v_cvt_pk_bf16_f32 v148, v142, v143
	v_cvt_pk_bf16_f32 v149, v144, v145
	global_store_dwordx2 v242, v[148:149], s[24:25] offset:256
	v_add_u32_e32 v243, 0x10400, v168
	v_mul_f32_e32 v142, v96, v134
	v_mul_f32_e32 v143, v88, v135
	v_mul_f32_e32 v144, v80, v136
	v_mul_f32_e32 v145, v72, v137
	v_cvt_pk_bf16_f32 v150, v142, v143
	v_cvt_pk_bf16_f32 v151, v144, v145
	global_store_dwordx2 v243, v[150:151], s[24:25] offset:256
	v_add_u32_e32 v244, 0x18600, v168
	v_mul_f32_e32 v142, v97, v134
	v_mul_f32_e32 v143, v89, v135
	v_mul_f32_e32 v144, v81, v136
	v_mul_f32_e32 v145, v73, v137
	v_cvt_pk_bf16_f32 v152, v142, v143
	v_cvt_pk_bf16_f32 v153, v144, v145
	global_store_dwordx2 v244, v[152:153], s[24:25] offset:256
	v_add_u32_e32 v245, 0x82000, v168
	v_mul_f32_e32 v142, v90, v134
	v_mul_f32_e32 v143, v82, v135
	v_mul_f32_e32 v144, v74, v136
	v_mul_f32_e32 v145, v66, v137
	v_cvt_pk_bf16_f32 v146, v142, v143
	v_cvt_pk_bf16_f32 v147, v144, v145
	global_store_dwordx2 v245, v[146:147], s[24:25] offset:256
	v_add_u32_e32 v234, 0x8a200, v168
	v_mul_f32_e32 v142, v91, v134
	v_mul_f32_e32 v143, v83, v135
	v_mul_f32_e32 v144, v75, v136
	v_mul_f32_e32 v145, v67, v137
	v_cvt_pk_bf16_f32 v148, v142, v143
	v_cvt_pk_bf16_f32 v149, v144, v145
	global_store_dwordx2 v234, v[148:149], s[24:25] offset:256
	v_add_u32_e32 v235, 0x92400, v168
	v_mul_f32_e32 v142, v92, v134
	v_mul_f32_e32 v143, v84, v135
	v_mul_f32_e32 v144, v76, v136
	v_mul_f32_e32 v145, v68, v137
	v_cvt_pk_bf16_f32 v150, v142, v143
	v_cvt_pk_bf16_f32 v151, v144, v145
	global_store_dwordx2 v235, v[150:151], s[24:25] offset:256
	v_add_u32_e32 v236, 0x9a600, v168
	v_mul_f32_e32 v142, v93, v134
	v_mul_f32_e32 v143, v85, v135
	v_mul_f32_e32 v144, v77, v136
	v_mul_f32_e32 v145, v69, v137
	v_cvt_pk_bf16_f32 v152, v142, v143
	v_cvt_pk_bf16_f32 v153, v144, v145
	global_store_dwordx2 v236, v[152:153], s[24:25] offset:256
	v_mul_f32_e32 v142, v94, v138
	v_mul_f32_e32 v143, v86, v139
	v_mul_f32_e32 v144, v78, v140
	v_mul_f32_e32 v145, v70, v141
	v_cvt_pk_bf16_f32 v146, v142, v143
	v_cvt_pk_bf16_f32 v147, v144, v145
	global_store_dwordx2 v168, v[146:147], s[82:83] offset:256
	v_add_u32_e32 v237, 0x8200, v168
	v_mul_f32_e32 v142, v95, v138
	v_mul_f32_e32 v143, v87, v139
	v_mul_f32_e32 v144, v79, v140
	v_mul_f32_e32 v145, v71, v141
	v_cvt_pk_bf16_f32 v148, v142, v143
	v_cvt_pk_bf16_f32 v149, v144, v145
	global_store_dwordx2 v237, v[148:149], s[82:83] offset:256
	v_add_u32_e32 v242, 0x10400, v168
	v_mul_f32_e32 v142, v96, v138
	v_mul_f32_e32 v143, v88, v139
	v_mul_f32_e32 v144, v80, v140
	v_mul_f32_e32 v145, v72, v141
	v_cvt_pk_bf16_f32 v150, v142, v143
	v_cvt_pk_bf16_f32 v151, v144, v145
	global_store_dwordx2 v242, v[150:151], s[82:83] offset:256
	v_add_u32_e32 v243, 0x18600, v168
	v_mul_f32_e32 v142, v97, v138
	v_mul_f32_e32 v143, v89, v139
	v_mul_f32_e32 v144, v81, v140
	v_mul_f32_e32 v145, v73, v141
	v_cvt_pk_bf16_f32 v152, v142, v143
	v_cvt_pk_bf16_f32 v153, v144, v145
	global_store_dwordx2 v243, v[152:153], s[82:83] offset:256
	v_add_u32_e32 v244, 0x82000, v168
	v_mul_f32_e32 v142, v90, v138
	v_mul_f32_e32 v143, v82, v139
	v_mul_f32_e32 v144, v74, v140
	v_mul_f32_e32 v145, v66, v141
	v_cvt_pk_bf16_f32 v146, v142, v143
	v_cvt_pk_bf16_f32 v147, v144, v145
	global_store_dwordx2 v244, v[146:147], s[82:83] offset:256
	v_add_u32_e32 v245, 0x8a200, v168
	v_mul_f32_e32 v142, v91, v138
	v_mul_f32_e32 v143, v83, v139
	v_mul_f32_e32 v144, v75, v140
	v_mul_f32_e32 v145, v67, v141
	v_cvt_pk_bf16_f32 v148, v142, v143
	v_cvt_pk_bf16_f32 v149, v144, v145
	global_store_dwordx2 v245, v[148:149], s[82:83] offset:256
	v_add_u32_e32 v234, 0x92400, v168
	v_mul_f32_e32 v142, v92, v138
	v_mul_f32_e32 v143, v84, v139
	v_mul_f32_e32 v144, v76, v140
	v_mul_f32_e32 v145, v68, v141
	v_cvt_pk_bf16_f32 v150, v142, v143
	v_cvt_pk_bf16_f32 v151, v144, v145
	global_store_dwordx2 v234, v[150:151], s[82:83] offset:256
	v_add_u32_e32 v235, 0x9a600, v168
	v_mul_f32_e32 v142, v93, v138
	v_mul_f32_e32 v143, v85, v139
	v_mul_f32_e32 v144, v77, v140
	v_mul_f32_e32 v145, v69, v141
	v_cvt_pk_bf16_f32 v152, v142, v143
	v_cvt_pk_bf16_f32 v153, v144, v145
	global_store_dwordx2 v235, v[152:153], s[82:83] offset:256
.Lip0_a1_nokt:
.Lip0_end:
	s_add_i32 s3, s3, 0x80
	s_and_b32 s12, s98, 10
	s_cbranch_scc0 .Lip1_end
	s_cmpk_gt_i32 s3, 0xb7f
	s_cbranch_scc1 .Lip1_end
	s_lshl_b32 s12, s3, 1
	v_add_u32_e32 v169, s12, v167
	s_add_i32 s0, s3, 0xfffffc00
	s_add_i32 s1, s3, 0xfffff780
	s_min_u32 s12, s0, s1
	s_cmpk_lt_u32 s12, 0x180
	s_cbranch_scc1 .Lip1_V
	s_add_i32 s12, s3, 0xfffffa80
	s_cmpk_lt_u32 s12, 0x300
	s_cbranch_scc1 .Lip1_R
	s_add_i32 s12, s3, 0xffffff00
	s_cmpk_lt_u32 s12, 0x180
	s_cbranch_scc0 .Lip1_nonq
	v_mul_f32_e32 v62, 0x3e38aa3b, v62
	v_mul_f32_e32 v63, 0x3e38aa3b, v63
	v_mul_f32_e32 v64, 0x3e38aa3b, v64
	v_mul_f32_e32 v65, 0x3e38aa3b, v65
	v_mul_f32_e32 v58, 0x3e38aa3b, v58
	v_mul_f32_e32 v59, 0x3e38aa3b, v59
	v_mul_f32_e32 v60, 0x3e38aa3b, v60
	v_mul_f32_e32 v61, 0x3e38aa3b, v61
	v_mul_f32_e32 v54, 0x3e38aa3b, v54
	v_mul_f32_e32 v55, 0x3e38aa3b, v55
	v_mul_f32_e32 v56, 0x3e38aa3b, v56
	v_mul_f32_e32 v57, 0x3e38aa3b, v57
	v_mul_f32_e32 v50, 0x3e38aa3b, v50
	v_mul_f32_e32 v51, 0x3e38aa3b, v51
	v_mul_f32_e32 v52, 0x3e38aa3b, v52
	v_mul_f32_e32 v53, 0x3e38aa3b, v53
	v_mul_f32_e32 v46, 0x3e38aa3b, v46
	v_mul_f32_e32 v47, 0x3e38aa3b, v47
	v_mul_f32_e32 v48, 0x3e38aa3b, v48
	v_mul_f32_e32 v49, 0x3e38aa3b, v49
	v_mul_f32_e32 v42, 0x3e38aa3b, v42
	v_mul_f32_e32 v43, 0x3e38aa3b, v43
	v_mul_f32_e32 v44, 0x3e38aa3b, v44
	v_mul_f32_e32 v45, 0x3e38aa3b, v45
	v_mul_f32_e32 v38, 0x3e38aa3b, v38
	v_mul_f32_e32 v39, 0x3e38aa3b, v39
	v_mul_f32_e32 v40, 0x3e38aa3b, v40
	v_mul_f32_e32 v41, 0x3e38aa3b, v41
	v_mul_f32_e32 v34, 0x3e38aa3b, v34
	v_mul_f32_e32 v35, 0x3e38aa3b, v35
	v_mul_f32_e32 v36, 0x3e38aa3b, v36
	v_mul_f32_e32 v37, 0x3e38aa3b, v37
	v_mul_f32_e32 v30, 0x3e38aa3b, v30
	v_mul_f32_e32 v31, 0x3e38aa3b, v31
	v_mul_f32_e32 v32, 0x3e38aa3b, v32
	v_mul_f32_e32 v33, 0x3e38aa3b, v33
	v_mul_f32_e32 v26, 0x3e38aa3b, v26
	v_mul_f32_e32 v27, 0x3e38aa3b, v27
	v_mul_f32_e32 v28, 0x3e38aa3b, v28
	v_mul_f32_e32 v29, 0x3e38aa3b, v29
	v_mul_f32_e32 v22, 0x3e38aa3b, v22
	v_mul_f32_e32 v23, 0x3e38aa3b, v23
	v_mul_f32_e32 v24, 0x3e38aa3b, v24
	v_mul_f32_e32 v25, 0x3e38aa3b, v25
	v_mul_f32_e32 v18, 0x3e38aa3b, v18
	v_mul_f32_e32 v19, 0x3e38aa3b, v19
	v_mul_f32_e32 v20, 0x3e38aa3b, v20
	v_mul_f32_e32 v21, 0x3e38aa3b, v21
	v_mul_f32_e32 v14, 0x3e38aa3b, v14
	v_mul_f32_e32 v15, 0x3e38aa3b, v15
	v_mul_f32_e32 v16, 0x3e38aa3b, v16
	v_mul_f32_e32 v17, 0x3e38aa3b, v17
	v_mul_f32_e32 v10, 0x3e38aa3b, v10
	v_mul_f32_e32 v11, 0x3e38aa3b, v11
	v_mul_f32_e32 v12, 0x3e38aa3b, v12
	v_mul_f32_e32 v13, 0x3e38aa3b, v13
	v_mul_f32_e32 v6, 0x3e38aa3b, v6
	v_mul_f32_e32 v7, 0x3e38aa3b, v7
	v_mul_f32_e32 v8, 0x3e38aa3b, v8
	v_mul_f32_e32 v9, 0x3e38aa3b, v9
	v_mul_f32_e32 v2, 0x3e38aa3b, v2
	v_mul_f32_e32 v3, 0x3e38aa3b, v3
	v_mul_f32_e32 v4, 0x3e38aa3b, v4
	v_mul_f32_e32 v5, 0x3e38aa3b, v5

.Lip1_nogate:
	s_bitcmp1_b32 s98, 1
	s_cbranch_scc0 .Lip1_ps0
	v_cvt_pk_bf16_f32 v138, v62, v63
	v_cvt_pk_bf16_f32 v139, v64, v65
	global_store_dwordx2 v169, v[138:139], s[60:61]
	v_cvt_pk_bf16_f32 v140, v58, v59
	v_cvt_pk_bf16_f32 v141, v60, v61
	global_store_dwordx2 v169, v[140:141], s[60:61] offset:32
	v_add_u32_e32 v170, 0x1700, v169
	v_cvt_pk_bf16_f32 v142, v54, v55
	v_cvt_pk_bf16_f32 v143, v56, v57
	global_store_dwordx2 v170, v[142:143], s[60:61]
	v_cvt_pk_bf16_f32 v144, v50, v51
	v_cvt_pk_bf16_f32 v145, v52, v53
	global_store_dwordx2 v170, v[144:145], s[60:61] offset:32
	v_add_u32_e32 v171, 0x2e00, v169
	v_cvt_pk_bf16_f32 v146, v46, v47
	v_cvt_pk_bf16_f32 v147, v48, v49
	global_store_dwordx2 v171, v[146:147], s[60:61]
	v_cvt_pk_bf16_f32 v148, v42, v43
	v_cvt_pk_bf16_f32 v149, v44, v45
	global_store_dwordx2 v171, v[148:149], s[60:61] offset:32
	v_add_u32_e32 v172, 0x4500, v169
	v_cvt_pk_bf16_f32 v150, v38, v39
	v_cvt_pk_bf16_f32 v151, v40, v41
	global_store_dwordx2 v172, v[150:151], s[60:61]
	v_cvt_pk_bf16_f32 v152, v34, v35
	v_cvt_pk_bf16_f32 v153, v36, v37
	global_store_dwordx2 v172, v[152:153], s[60:61] offset:32
.Lip1_ps0:
	s_bitcmp1_b32 s98, 3
	s_cbranch_scc0 .Lip1_ps1
	v_add_u32_e32 v173, 0xb8000, v169
	v_cvt_pk_bf16_f32 v138, v30, v31
	v_cvt_pk_bf16_f32 v139, v32, v33
	global_store_dwordx2 v173, v[138:139], s[60:61]
	v_cvt_pk_bf16_f32 v140, v26, v27
	v_cvt_pk_bf16_f32 v141, v28, v29
	global_store_dwordx2 v173, v[140:141], s[60:61] offset:32
	v_add_u32_e32 v174, 0xb9700, v169
	v_cvt_pk_bf16_f32 v142, v22, v23
	v_cvt_pk_bf16_f32 v143, v24, v25
	global_store_dwordx2 v174, v[142:143], s[60:61]
	v_cvt_pk_bf16_f32 v144, v18, v19
	v_cvt_pk_bf16_f32 v145, v20, v21
	global_store_dwordx2 v174, v[144:145], s[60:61] offset:32
	v_add_u32_e32 v175, 0xbae00, v169
	v_cvt_pk_bf16_f32 v146, v14, v15
	v_cvt_pk_bf16_f32 v147, v16, v17
	global_store_dwordx2 v175, v[146:147], s[60:61]
	v_cvt_pk_bf16_f32 v148, v10, v11
	v_cvt_pk_bf16_f32 v149, v12, v13
	global_store_dwordx2 v175, v[148:149], s[60:61] offset:32
	v_add_u32_e32 v176, 0xbc500, v169
	v_cvt_pk_bf16_f32 v150, v6, v7
	v_cvt_pk_bf16_f32 v151, v8, v9
	global_store_dwordx2 v176, v[150:151], s[60:61]
	v_cvt_pk_bf16_f32 v152, v2, v3
	v_cvt_pk_bf16_f32 v153, v4, v5
	global_store_dwordx2 v176, v[152:153], s[60:61] offset:32

.Lip1_V:
	s_cmpk_lt_u32 s0, 0x180
	s_cbranch_scc0 .Lip1_RV
	s_lshr_b32 s12, s0, 6
	s_mul_i32 s12, s12, 0x208000
	s_and_b32 s15, s0, 63
	s_lshl_b32 s15, s15, 7
	s_add_u32 s12, s12, s15
	s_lshl_b32 s15, s2, 7
	s_add_u32 s12, s12, s15
	s_add_u32 s12, s12, 0x12174000
	s_add_u32 s64, s8, s12
	s_addc_u32 s65, s9, 0
	v_lshlrev_b32_e32 v168, 7, v228
	v_lshl_add_u32 v168, v226, 3, v168
	v_add_u32_e32 v170, 0x4000, v168
	s_bitcmp1_b32 s98, 1
	s_cbranch_scc0 .Lip1_nv0
	v_cvt_pk_bf16_f32 v138, v62, v54
	v_cvt_pk_bf16_f32 v139, v46, v38
	global_store_dwordx2 v168, v[138:139], s[64:65]
	v_cvt_pk_bf16_f32 v140, v63, v55
	v_cvt_pk_bf16_f32 v141, v47, v39
	global_store_dwordx2 v168, v[140:141], s[64:65] offset:128
	v_cvt_pk_bf16_f32 v142, v64, v56
	v_cvt_pk_bf16_f32 v143, v48, v40
	global_store_dwordx2 v168, v[142:143], s[64:65] offset:256
	v_cvt_pk_bf16_f32 v144, v65, v57
	v_cvt_pk_bf16_f32 v145, v49, v41
	global_store_dwordx2 v168, v[144:145], s[64:65] offset:384
	v_cvt_pk_bf16_f32 v146, v58, v50
	v_cvt_pk_bf16_f32 v147, v42, v34
	global_store_dwordx2 v168, v[146:147], s[64:65] offset:2048
	v_cvt_pk_bf16_f32 v148, v59, v51
	v_cvt_pk_bf16_f32 v149, v43, v35
	global_store_dwordx2 v168, v[148:149], s[64:65] offset:2176
	v_cvt_pk_bf16_f32 v150, v60, v52
	v_cvt_pk_bf16_f32 v151, v44, v36
	global_store_dwordx2 v168, v[150:151], s[64:65] offset:2304
	v_cvt_pk_bf16_f32 v152, v61, v53
	v_cvt_pk_bf16_f32 v153, v45, v37
	global_store_dwordx2 v168, v[152:153], s[64:65] offset:2432
.Lip1_nv0:
	s_bitcmp1_b32 s98, 3
	s_cbranch_scc0 .Lip1_nv1
	v_cvt_pk_bf16_f32 v138, v30, v22
	v_cvt_pk_bf16_f32 v139, v14, v6
	global_store_dwordx2 v170, v[138:139], s[64:65]
	v_cvt_pk_bf16_f32 v140, v31, v23
	v_cvt_pk_bf16_f32 v141, v15, v7
	global_store_dwordx2 v170, v[140:141], s[64:65] offset:128
	v_cvt_pk_bf16_f32 v142, v32, v24
	v_cvt_pk_bf16_f32 v143, v16, v8
	global_store_dwordx2 v170, v[142:143], s[64:65] offset:256
	v_cvt_pk_bf16_f32 v144, v33, v25
	v_cvt_pk_bf16_f32 v145, v17, v9
	global_store_dwordx2 v170, v[144:145], s[64:65] offset:384
	v_cvt_pk_bf16_f32 v146, v26, v18
	v_cvt_pk_bf16_f32 v147, v10, v2
	global_store_dwordx2 v170, v[146:147], s[64:65] offset:2048
	v_cvt_pk_bf16_f32 v148, v27, v19
	v_cvt_pk_bf16_f32 v149, v11, v3
	global_store_dwordx2 v170, v[148:149], s[64:65] offset:2176
	v_cvt_pk_bf16_f32 v150, v28, v20
	v_cvt_pk_bf16_f32 v151, v12, v4
	global_store_dwordx2 v170, v[150:151], s[64:65] offset:2304
	v_cvt_pk_bf16_f32 v152, v29, v21
	v_cvt_pk_bf16_f32 v153, v13, v5
	global_store_dwordx2 v170, v[152:153], s[64:65] offset:2432

.Lip1_RV:
	s_cmpk_lt_u32 s0, 0x180
	s_cselect_b32 s12, s0, s1
	s_mov_b32 s15, 0x12da4000
	s_cselect_b32 s15, 0x12174000, s15
	s_add_u32 s64, s8, s15
	s_addc_u32 s65, s9, 0
	v_add_u32_e32 v168, s12, v228
	v_mul_u32_u24_e32 v168, 0x8200, v168
	v_lshl_add_u32 v168, v166, 1, v168
	s_bitcmp1_b32 s98, 1
	s_cbranch_scc0 .Lip1_rv0
	v_cvt_pk_bf16_f32 v138, v62, v54
	v_cvt_pk_bf16_f32 v139, v46, v38
	global_store_dwordx2 v168, v[138:139], s[64:65]
	v_add_u32_e32 v170, 0x8200, v168
	v_cvt_pk_bf16_f32 v140, v63, v55
	v_cvt_pk_bf16_f32 v141, v47, v39
	global_store_dwordx2 v170, v[140:141], s[64:65]
	v_add_u32_e32 v171, 0x10400, v168
	v_cvt_pk_bf16_f32 v142, v64, v56
	v_cvt_pk_bf16_f32 v143, v48, v40
	global_store_dwordx2 v171, v[142:143], s[64:65]
	v_add_u32_e32 v172, 0x18600, v168
	v_cvt_pk_bf16_f32 v144, v65, v57
	v_cvt_pk_bf16_f32 v145, v49, v41
	global_store_dwordx2 v172, v[144:145], s[64:65]
	v_add_u32_e32 v173, 0x82000, v168
	v_cvt_pk_bf16_f32 v146, v58, v50
	v_cvt_pk_bf16_f32 v147, v42, v34
	global_store_dwordx2 v173, v[146:147], s[64:65]
	v_add_u32_e32 v174, 0x8a200, v168
	v_cvt_pk_bf16_f32 v148, v59, v51
	v_cvt_pk_bf16_f32 v149, v43, v35
	global_store_dwordx2 v174, v[148:149], s[64:65]
	v_add_u32_e32 v175, 0x92400, v168
	v_cvt_pk_bf16_f32 v150, v60, v52
	v_cvt_pk_bf16_f32 v151, v44, v36
	global_store_dwordx2 v175, v[150:151], s[64:65]
	v_add_u32_e32 v176, 0x9a600, v168
	v_cvt_pk_bf16_f32 v152, v61, v53
	v_cvt_pk_bf16_f32 v153, v45, v37
	global_store_dwordx2 v176, v[152:153], s[64:65]
.Lip1_rv0:
	s_bitcmp1_b32 s98, 3
	s_cbranch_scc0 .Lip1_rv1
	v_cvt_pk_bf16_f32 v138, v30, v22
	v_cvt_pk_bf16_f32 v139, v14, v6
	global_store_dwordx2 v168, v[138:139], s[64:65] offset:256
	v_add_u32_e32 v177, 0x8200, v168
	v_cvt_pk_bf16_f32 v140, v31, v23
	v_cvt_pk_bf16_f32 v141, v15, v7
	global_store_dwordx2 v177, v[140:141], s[64:65] offset:256
	v_add_u32_e32 v170, 0x10400, v168
	v_cvt_pk_bf16_f32 v142, v32, v24
	v_cvt_pk_bf16_f32 v143, v16, v8
	global_store_dwordx2 v170, v[142:143], s[64:65] offset:256
	v_add_u32_e32 v171, 0x18600, v168
	v_cvt_pk_bf16_f32 v144, v33, v25
	v_cvt_pk_bf16_f32 v145, v17, v9
	global_store_dwordx2 v171, v[144:145], s[64:65] offset:256
	v_add_u32_e32 v172, 0x82000, v168
	v_cvt_pk_bf16_f32 v146, v26, v18
	v_cvt_pk_bf16_f32 v147, v10, v2
	global_store_dwordx2 v172, v[146:147], s[64:65] offset:256
	v_add_u32_e32 v173, 0x8a200, v168
	v_cvt_pk_bf16_f32 v148, v27, v19
	v_cvt_pk_bf16_f32 v149, v11, v3
	global_store_dwordx2 v173, v[148:149], s[64:65] offset:256
	v_add_u32_e32 v174, 0x92400, v168
	v_cvt_pk_bf16_f32 v150, v28, v20
	v_cvt_pk_bf16_f32 v151, v12, v4
	global_store_dwordx2 v174, v[150:151], s[64:65] offset:256
	v_add_u32_e32 v175, 0x9a600, v168
	v_cvt_pk_bf16_f32 v152, v29, v21
	v_cvt_pk_bf16_f32 v153, v13, v5
	global_store_dwordx2 v175, v[152:153], s[64:65] offset:256
.Lip1_rv1:
	s_branch .Lip1_end
.Lip1_R:
	s_cmpk_gt_i32 s3, 0x6ff
	s_cselect_b32 s46, 1, 0
	v_lshlrev_b32_e32 v130, 8, v226
	v_lshl_add_u32 v130, v228, 2, v130
	v_lshl_add_u32 v131, v228, 2, s2
	s_bitcmp1_b32 s3, 5
	s_cselect_b32 s12, 64, 0
	s_cselect_b32 s15, 0, 0x80
	s_cselect_b64 vcc, -1, 0
	s_add_u32 s16, s44, 0x4000
	s_addc_u32 s17, s45, 0
	v_cndmask_b32_e32 v130, v131, v130, vcc
	v_add_u32_e32 v131, s12, v130
	v_add_u32_e32 v132, s12, v131
	v_add_u32_e32 v133, s12, v132
	s_cmp_lg_u32 s47, 0
	s_cbranch_scc0 .Lip1_Rnoload
	global_load_dwordx4 v[170:173], v130, s[44:45]
	global_load_dwordx4 v[186:189], v130, s[16:17]
	global_load_dwordx4 v[174:177], v131, s[44:45]
	global_load_dwordx4 v[190:193], v131, s[16:17]
	global_load_dwordx4 v[178:181], v132, s[44:45]
	global_load_dwordx4 v[194:197], v132, s[16:17]
	global_load_dwordx4 v[182:185], v133, s[44:45]
	global_load_dwordx4 v[198:201], v133, s[16:17]

.Lip1_a0_noscale:
	s_bitcmp1_b32 s98, 1
	s_cbranch_scc0 .Lip1_a0_nokt
	v_cvt_pk_bf16_f32 v146, v62, v63
	v_cvt_pk_bf16_f32 v147, v64, v65
	global_store_dwordx2 v169, v[146:147], s[60:61]
	v_cvt_pk_bf16_f32 v148, v58, v59
	v_cvt_pk_bf16_f32 v149, v60, v61
	global_store_dwordx2 v169, v[148:149], s[60:61] offset:32
	v_add_u32_e32 v234, 0x1700, v169
	v_cvt_pk_bf16_f32 v150, v54, v55
	v_cvt_pk_bf16_f32 v151, v56, v57
	global_store_dwordx2 v234, v[150:151], s[60:61]
	v_cvt_pk_bf16_f32 v152, v50, v51
	v_cvt_pk_bf16_f32 v153, v52, v53
	global_store_dwordx2 v234, v[152:153], s[60:61] offset:32
	v_add_u32_e32 v235, 0x2e00, v169
	v_cvt_pk_bf16_f32 v146, v46, v47
	v_cvt_pk_bf16_f32 v147, v48, v49
	global_store_dwordx2 v235, v[146:147], s[60:61]
	v_cvt_pk_bf16_f32 v148, v42, v43
	v_cvt_pk_bf16_f32 v149, v44, v45
	global_store_dwordx2 v235, v[148:149], s[60:61] offset:32
	v_add_u32_e32 v236, 0x4500, v169
	v_cvt_pk_bf16_f32 v150, v38, v39
	v_cvt_pk_bf16_f32 v151, v40, v41
	global_store_dwordx2 v236, v[150:151], s[60:61]
	v_cvt_pk_bf16_f32 v152, v34, v35
	v_cvt_pk_bf16_f32 v153, v36, v37
	global_store_dwordx2 v236, v[152:153], s[60:61] offset:32
	s_cmp_lg_u32 s46, 0
	s_cbranch_scc0 .Lip1_a0_nokt
	v_mul_f32_e32 v142, v62, v134
	v_mul_f32_e32 v143, v54, v135
	v_mul_f32_e32 v144, v46, v136
	v_mul_f32_e32 v145, v38, v137
	v_cvt_pk_bf16_f32 v146, v142, v143
	v_cvt_pk_bf16_f32 v147, v144, v145
	global_store_dwordx2 v168, v[146:147], s[24:25]
	v_add_u32_e32 v237, 0x8200, v168
	v_mul_f32_e32 v142, v63, v134
	v_mul_f32_e32 v143, v55, v135
	v_mul_f32_e32 v144, v47, v136
	v_mul_f32_e32 v145, v39, v137
	v_cvt_pk_bf16_f32 v148, v142, v143
	v_cvt_pk_bf16_f32 v149, v144, v145
	global_store_dwordx2 v237, v[148:149], s[24:25]
	v_add_u32_e32 v242, 0x10400, v168
	v_mul_f32_e32 v142, v64, v134
	v_mul_f32_e32 v143, v56, v135
	v_mul_f32_e32 v144, v48, v136
	v_mul_f32_e32 v145, v40, v137
	v_cvt_pk_bf16_f32 v150, v142, v143
	v_cvt_pk_bf16_f32 v151, v144, v145
	global_store_dwordx2 v242, v[150:151], s[24:25]
	v_add_u32_e32 v243, 0x18600, v168
	v_mul_f32_e32 v142, v65, v134
	v_mul_f32_e32 v143, v57, v135
	v_mul_f32_e32 v144, v49, v136
	v_mul_f32_e32 v145, v41, v137
	v_cvt_pk_bf16_f32 v152, v142, v143
	v_cvt_pk_bf16_f32 v153, v144, v145
	global_store_dwordx2 v243, v[152:153], s[24:25]
	v_add_u32_e32 v244, 0x82000, v168
	v_mul_f32_e32 v142, v58, v134
	v_mul_f32_e32 v143, v50, v135
	v_mul_f32_e32 v144, v42, v136
	v_mul_f32_e32 v145, v34, v137
	v_cvt_pk_bf16_f32 v146, v142, v143
	v_cvt_pk_bf16_f32 v147, v144, v145
	global_store_dwordx2 v244, v[146:147], s[24:25]
	v_add_u32_e32 v245, 0x8a200, v168
	v_mul_f32_e32 v142, v59, v134
	v_mul_f32_e32 v143, v51, v135
	v_mul_f32_e32 v144, v43, v136
	v_mul_f32_e32 v145, v35, v137
	v_cvt_pk_bf16_f32 v148, v142, v143
	v_cvt_pk_bf16_f32 v149, v144, v145
	global_store_dwordx2 v245, v[148:149], s[24:25]
	v_add_u32_e32 v234, 0x92400, v168
	v_mul_f32_e32 v142, v60, v134
	v_mul_f32_e32 v143, v52, v135
	v_mul_f32_e32 v144, v44, v136
	v_mul_f32_e32 v145, v36, v137
	v_cvt_pk_bf16_f32 v150, v142, v143
	v_cvt_pk_bf16_f32 v151, v144, v145
	global_store_dwordx2 v234, v[150:151], s[24:25]
	v_add_u32_e32 v235, 0x9a600, v168
	v_mul_f32_e32 v142, v61, v134
	v_mul_f32_e32 v143, v53, v135
	v_mul_f32_e32 v144, v45, v136
	v_mul_f32_e32 v145, v37, v137
	v_cvt_pk_bf16_f32 v152, v142, v143
	v_cvt_pk_bf16_f32 v153, v144, v145
	global_store_dwordx2 v235, v[152:153], s[24:25]
	v_mul_f32_e32 v142, v62, v138
	v_mul_f32_e32 v143, v54, v139
	v_mul_f32_e32 v144, v46, v140
	v_mul_f32_e32 v145, v38, v141
	v_cvt_pk_bf16_f32 v146, v142, v143
	v_cvt_pk_bf16_f32 v147, v144, v145
	global_store_dwordx2 v168, v[146:147], s[82:83]
	v_add_u32_e32 v236, 0x8200, v168
	v_mul_f32_e32 v142, v63, v138
	v_mul_f32_e32 v143, v55, v139
	v_mul_f32_e32 v144, v47, v140
	v_mul_f32_e32 v145, v39, v141
	v_cvt_pk_bf16_f32 v148, v142, v143
	v_cvt_pk_bf16_f32 v149, v144, v145
	global_store_dwordx2 v236, v[148:149], s[82:83]
	v_add_u32_e32 v237, 0x10400, v168
	v_mul_f32_e32 v142, v64, v138
	v_mul_f32_e32 v143, v56, v139
	v_mul_f32_e32 v144, v48, v140
	v_mul_f32_e32 v145, v40, v141
	v_cvt_pk_bf16_f32 v150, v142, v143
	v_cvt_pk_bf16_f32 v151, v144, v145
	global_store_dwordx2 v237, v[150:151], s[82:83]
	v_add_u32_e32 v242, 0x18600, v168
	v_mul_f32_e32 v142, v65, v138
	v_mul_f32_e32 v143, v57, v139
	v_mul_f32_e32 v144, v49, v140
	v_mul_f32_e32 v145, v41, v141
	v_cvt_pk_bf16_f32 v152, v142, v143
	v_cvt_pk_bf16_f32 v153, v144, v145
	global_store_dwordx2 v242, v[152:153], s[82:83]
	v_add_u32_e32 v243, 0x82000, v168
	v_mul_f32_e32 v142, v58, v138
	v_mul_f32_e32 v143, v50, v139
	v_mul_f32_e32 v144, v42, v140
	v_mul_f32_e32 v145, v34, v141
	v_cvt_pk_bf16_f32 v146, v142, v143
	v_cvt_pk_bf16_f32 v147, v144, v145
	global_store_dwordx2 v243, v[146:147], s[82:83]
	v_add_u32_e32 v244, 0x8a200, v168
	v_mul_f32_e32 v142, v59, v138
	v_mul_f32_e32 v143, v51, v139
	v_mul_f32_e32 v144, v43, v140
	v_mul_f32_e32 v145, v35, v141
	v_cvt_pk_bf16_f32 v148, v142, v143
	v_cvt_pk_bf16_f32 v149, v144, v145
	global_store_dwordx2 v244, v[148:149], s[82:83]
	v_add_u32_e32 v245, 0x92400, v168
	v_mul_f32_e32 v142, v60, v138
	v_mul_f32_e32 v143, v52, v139
	v_mul_f32_e32 v144, v44, v140
	v_mul_f32_e32 v145, v36, v141
	v_cvt_pk_bf16_f32 v150, v142, v143
	v_cvt_pk_bf16_f32 v151, v144, v145
	global_store_dwordx2 v245, v[150:151], s[82:83]
	v_add_u32_e32 v234, 0x9a600, v168
	v_mul_f32_e32 v142, v61, v138
	v_mul_f32_e32 v143, v53, v139
	v_mul_f32_e32 v144, v45, v140
	v_mul_f32_e32 v145, v37, v141
	v_cvt_pk_bf16_f32 v152, v142, v143
	v_cvt_pk_bf16_f32 v153, v144, v145
	global_store_dwordx2 v234, v[152:153], s[82:83]

.Lip1_a1_noscale:
	s_bitcmp1_b32 s98, 3
	s_cbranch_scc0 .Lip1_a1_nokt
	v_add_u32_e32 v234, 0xb8000, v169
	v_cvt_pk_bf16_f32 v146, v30, v31
	v_cvt_pk_bf16_f32 v147, v32, v33
	global_store_dwordx2 v234, v[146:147], s[60:61]
	v_cvt_pk_bf16_f32 v148, v26, v27
	v_cvt_pk_bf16_f32 v149, v28, v29
	global_store_dwordx2 v234, v[148:149], s[60:61] offset:32
	v_add_u32_e32 v235, 0xb9700, v169
	v_cvt_pk_bf16_f32 v150, v22, v23
	v_cvt_pk_bf16_f32 v151, v24, v25
	global_store_dwordx2 v235, v[150:151], s[60:61]
	v_cvt_pk_bf16_f32 v152, v18, v19
	v_cvt_pk_bf16_f32 v153, v20, v21
	global_store_dwordx2 v235, v[152:153], s[60:61] offset:32
	v_add_u32_e32 v236, 0xbae00, v169
	v_cvt_pk_bf16_f32 v146, v14, v15
	v_cvt_pk_bf16_f32 v147, v16, v17
	global_store_dwordx2 v236, v[146:147], s[60:61]
	v_cvt_pk_bf16_f32 v148, v10, v11
	v_cvt_pk_bf16_f32 v149, v12, v13
	global_store_dwordx2 v236, v[148:149], s[60:61] offset:32
	v_add_u32_e32 v237, 0xbc500, v169
	v_cvt_pk_bf16_f32 v150, v6, v7
	v_cvt_pk_bf16_f32 v151, v8, v9
	global_store_dwordx2 v237, v[150:151], s[60:61]
	v_cvt_pk_bf16_f32 v152, v2, v3
	v_cvt_pk_bf16_f32 v153, v4, v5
	global_store_dwordx2 v237, v[152:153], s[60:61] offset:32
	s_cmp_lg_u32 s46, 0
	s_cbranch_scc0 .Lip1_a1_nokt
	v_mul_f32_e32 v142, v30, v134
	v_mul_f32_e32 v143, v22, v135
	v_mul_f32_e32 v144, v14, v136
	v_mul_f32_e32 v145, v6, v137
	v_cvt_pk_bf16_f32 v146, v142, v143
	v_cvt_pk_bf16_f32 v147, v144, v145
	global_store_dwordx2 v168, v[146:147], s[24:25] offset:256
	v_add_u32_e32 v242, 0x8200, v168
	v_mul_f32_e32 v142, v31, v134
	v_mul_f32_e32 v143, v23, v135
	v_mul_f32_e32 v144, v15, v136
	v_mul_f32_e32 v145, v7, v137
	v_cvt_pk_bf16_f32 v148, v142, v143
	v_cvt_pk_bf16_f32 v149, v144, v145
	global_store_dwordx2 v242, v[148:149], s[24:25] offset:256
	v_add_u32_e32 v243, 0x10400, v168
	v_mul_f32_e32 v142, v32, v134
	v_mul_f32_e32 v143, v24, v135
	v_mul_f32_e32 v144, v16, v136
	v_mul_f32_e32 v145, v8, v137
	v_cvt_pk_bf16_f32 v150, v142, v143
	v_cvt_pk_bf16_f32 v151, v144, v145
	global_store_dwordx2 v243, v[150:151], s[24:25] offset:256
	v_add_u32_e32 v244, 0x18600, v168
	v_mul_f32_e32 v142, v33, v134
	v_mul_f32_e32 v143, v25, v135
	v_mul_f32_e32 v144, v17, v136
	v_mul_f32_e32 v145, v9, v137
	v_cvt_pk_bf16_f32 v152, v142, v143
	v_cvt_pk_bf16_f32 v153, v144, v145
	global_store_dwordx2 v244, v[152:153], s[24:25] offset:256
	v_add_u32_e32 v245, 0x82000, v168
	v_mul_f32_e32 v142, v26, v134
	v_mul_f32_e32 v143, v18, v135
	v_mul_f32_e32 v144, v10, v136
	v_mul_f32_e32 v145, v2, v137
	v_cvt_pk_bf16_f32 v146, v142, v143
	v_cvt_pk_bf16_f32 v147, v144, v145
	global_store_dwordx2 v245, v[146:147], s[24:25] offset:256
	v_add_u32_e32 v234, 0x8a200, v168
	v_mul_f32_e32 v142, v27, v134
	v_mul_f32_e32 v143, v19, v135
	v_mul_f32_e32 v144, v11, v136
	v_mul_f32_e32 v145, v3, v137
	v_cvt_pk_bf16_f32 v148, v142, v143
	v_cvt_pk_bf16_f32 v149, v144, v145
	global_store_dwordx2 v234, v[148:149], s[24:25] offset:256
	v_add_u32_e32 v235, 0x92400, v168
	v_mul_f32_e32 v142, v28, v134
	v_mul_f32_e32 v143, v20, v135
	v_mul_f32_e32 v144, v12, v136
	v_mul_f32_e32 v145, v4, v137
	v_cvt_pk_bf16_f32 v150, v142, v143
	v_cvt_pk_bf16_f32 v151, v144, v145
	global_store_dwordx2 v235, v[150:151], s[24:25] offset:256
	v_add_u32_e32 v236, 0x9a600, v168
	v_mul_f32_e32 v142, v29, v134
	v_mul_f32_e32 v143, v21, v135
	v_mul_f32_e32 v144, v13, v136
	v_mul_f32_e32 v145, v5, v137
	v_cvt_pk_bf16_f32 v152, v142, v143
	v_cvt_pk_bf16_f32 v153, v144, v145
	global_store_dwordx2 v236, v[152:153], s[24:25] offset:256
	v_mul_f32_e32 v142, v30, v138
	v_mul_f32_e32 v143, v22, v139
	v_mul_f32_e32 v144, v14, v140
	v_mul_f32_e32 v145, v6, v141
	v_cvt_pk_bf16_f32 v146, v142, v143
	v_cvt_pk_bf16_f32 v147, v144, v145
	global_store_dwordx2 v168, v[146:147], s[82:83] offset:256
	v_add_u32_e32 v237, 0x8200, v168
	v_mul_f32_e32 v142, v31, v138
	v_mul_f32_e32 v143, v23, v139
	v_mul_f32_e32 v144, v15, v140
	v_mul_f32_e32 v145, v7, v141
	v_cvt_pk_bf16_f32 v148, v142, v143
	v_cvt_pk_bf16_f32 v149, v144, v145
	global_store_dwordx2 v237, v[148:149], s[82:83] offset:256
	v_add_u32_e32 v242, 0x10400, v168
	v_mul_f32_e32 v142, v32, v138
	v_mul_f32_e32 v143, v24, v139
	v_mul_f32_e32 v144, v16, v140
	v_mul_f32_e32 v145, v8, v141
	v_cvt_pk_bf16_f32 v150, v142, v143
	v_cvt_pk_bf16_f32 v151, v144, v145
	global_store_dwordx2 v242, v[150:151], s[82:83] offset:256
	v_add_u32_e32 v243, 0x18600, v168
	v_mul_f32_e32 v142, v33, v138
	v_mul_f32_e32 v143, v25, v139
	v_mul_f32_e32 v144, v17, v140
	v_mul_f32_e32 v145, v9, v141
	v_cvt_pk_bf16_f32 v152, v142, v143
	v_cvt_pk_bf16_f32 v153, v144, v145
	global_store_dwordx2 v243, v[152:153], s[82:83] offset:256
	v_add_u32_e32 v244, 0x82000, v168
	v_mul_f32_e32 v142, v26, v138
	v_mul_f32_e32 v143, v18, v139
	v_mul_f32_e32 v144, v10, v140
	v_mul_f32_e32 v145, v2, v141
	v_cvt_pk_bf16_f32 v146, v142, v143
	v_cvt_pk_bf16_f32 v147, v144, v145
	global_store_dwordx2 v244, v[146:147], s[82:83] offset:256
	v_add_u32_e32 v245, 0x8a200, v168
	v_mul_f32_e32 v142, v27, v138
	v_mul_f32_e32 v143, v19, v139
	v_mul_f32_e32 v144, v11, v140
	v_mul_f32_e32 v145, v3, v141
	v_cvt_pk_bf16_f32 v148, v142, v143
	v_cvt_pk_bf16_f32 v149, v144, v145
	global_store_dwordx2 v245, v[148:149], s[82:83] offset:256
	v_add_u32_e32 v234, 0x92400, v168
	v_mul_f32_e32 v142, v28, v138
	v_mul_f32_e32 v143, v20, v139
	v_mul_f32_e32 v144, v12, v140
	v_mul_f32_e32 v145, v4, v141
	v_cvt_pk_bf16_f32 v150, v142, v143
	v_cvt_pk_bf16_f32 v151, v144, v145
	global_store_dwordx2 v234, v[150:151], s[82:83] offset:256
	v_add_u32_e32 v235, 0x9a600, v168
	v_mul_f32_e32 v142, v29, v138
	v_mul_f32_e32 v143, v21, v139
	v_mul_f32_e32 v144, v13, v140
	v_mul_f32_e32 v145, v5, v141
	v_cvt_pk_bf16_f32 v152, v142, v143
	v_cvt_pk_bf16_f32 v153, v144, v145
	global_store_dwordx2 v235, v[152:153], s[82:83] offset:256

.Lq_unit:
	s_ff1_i32_b32 s2, s98
	s_lshr_b32 s3, s2, 1
	s_and_b32 s2, s2, 1
	s_lshl_b32 s12, s3, 14
	s_xor_b32 s13, s12, 0x4000
	v_add_u32_e32 v190, s12, v233
	v_add_u32_e32 v192, s13, v233
	s_add_i32 s44, s54, s12
	s_add_i32 s46, s54, s13
	s_lshl_b32 s12, s2, 14
	s_xor_b32 s13, s12, 0x4000
	s_add_i32 s12, s12, 0x10000
	s_add_i32 s13, s13, 0x10000
	v_add_u32_e32 v191, s12, v227
	v_add_u32_e32 v193, s13, v227
	s_add_i32 s45, s54, s12
	s_add_i32 s47, s54, s13
	s_lshl_b32 s12, s3, 18
	s_lshl_b32 s13, s2, 18
	s_add_u32 s0, s0, 0xfffbff80
	s_addc_u32 s1, s1, -1
	s_add_u32 s0, s0, s12
	s_addc_u32 s1, s1, 0
	s_add_u32 s0, s0, 0x100
	s_addc_u32 s1, s1, 0
	s_add_u32 s16, s16, s13
	s_addc_u32 s17, s17, 0
	s_add_u32 s16, s16, 0x100
	s_addc_u32 s17, s17, 0
	s_add_u32 s2, s0, 0xffffff80
	s_addc_u32 s3, s1, -1
	s_add_i32 m0, s44, 0x8000
	s_nop 0
	global_load_lds_dwordx4 v250, s[2:3]
	s_add_i32 m0, s44, 0xa000
	s_nop 0
	global_load_lds_dwordx4 v251, s[2:3]
	s_waitcnt vmcnt(0)
	s_cmpk_gt_u32 s22, 0xff
	s_cbranch_scc1 .Lq_aligned
	s_barrier
.Lq_aligned:
	s_barrier
	s_add_i32 m0, s46, 0x0
	s_nop 0
	global_load_lds_dwordx4 v250, s[0:1]
	s_add_i32 m0, s46, 0x2000
	s_nop 0
	global_load_lds_dwordx4 v251, s[0:1]
	s_add_i32 m0, s47, 0x0
	s_nop 0
	global_load_lds_dwordx4 v0, s[16:17]
	s_add_i32 m0, s47, 0x2000
	s_nop 0
	global_load_lds_dwordx4 v154, s[16:17]
	s_add_u32 s0, s0, 0x80
	s_addc_u32 s1, s1, 0
	s_add_u32 s16, s16, 0x80
	s_addc_u32 s17, s17, 0
	s_add_i32 m0, s46, 0x8000
	s_nop 0
	global_load_lds_dwordx4 v250, s[0:1]
	s_add_i32 m0, s46, 0xa000
	s_nop 0
	global_load_lds_dwordx4 v251, s[0:1]
	s_add_i32 m0, s47, 0x8000
	s_nop 0
	global_load_lds_dwordx4 v0, s[16:17]
	s_add_i32 m0, s47, 0xa000
	s_nop 0
	global_load_lds_dwordx4 v154, s[16:17]
	s_add_u32 s0, s0, 0x80
	s_addc_u32 s1, s1, 0
	s_add_u32 s16, s16, 0x80
	s_addc_u32 s17, s17, 0
	ds_read_b128 v[130:133], v191 offset:0
	ds_read_b128 v[134:137], v191 offset:1024
	ds_read_b128 v[138:141], v191 offset:2048
	ds_read_b128 v[142:145], v191 offset:3072
	ds_read_b128 v[146:149], v190 offset:0
	ds_read_b128 v[150:153], v190 offset:1024
	ds_read_b128 v[166:169], v190 offset:2048
	ds_read_b128 v[170:173], v190 offset:3072
	ds_read_b128 v[174:177], v190 offset:4096
	ds_read_b128 v[178:181], v190 offset:5120
	ds_read_b128 v[182:185], v190 offset:6144
	ds_read_b128 v[186:189], v190 offset:7168
	s_waitcnt lgkmcnt(0)
	s_waitcnt vmcnt(8)
	s_barrier
	s_add_i32 m0, s44, 0x0
	s_nop 0
	global_load_lds_dwordx4 v250, s[0:1]
	s_add_i32 m0, s44, 0x2000
	s_nop 0
	global_load_lds_dwordx4 v251, s[0:1]
	s_add_i32 m0, s45, 0x0
	s_nop 0
	global_load_lds_dwordx4 v0, s[16:17]
	s_add_i32 m0, s45, 0x2000
	s_nop 0
	global_load_lds_dwordx4 v154, s[16:17]
	s_add_u32 s0, s0, 0x80
	s_addc_u32 s1, s1, 0
	s_add_u32 s16, s16, 0x80
	s_addc_u32 s17, s17, 0
	v_mfma_f32_16x16x32_bf16 v[126:129], v[130:133], v[146:149], v[126:129]
	v_mfma_f32_16x16x32_bf16 v[122:125], v[138:141], v[146:149], v[122:125]
	v_mfma_f32_16x16x32_bf16 v[118:121], v[130:133], v[166:169], v[118:121]
	v_mfma_f32_16x16x32_bf16 v[114:117], v[138:141], v[166:169], v[114:117]
	v_mfma_f32_16x16x32_bf16 v[110:113], v[130:133], v[174:177], v[110:113]
	v_mfma_f32_16x16x32_bf16 v[106:109], v[138:141], v[174:177], v[106:109]
	v_mfma_f32_16x16x32_bf16 v[102:105], v[130:133], v[182:185], v[102:105]
	v_mfma_f32_16x16x32_bf16 v[98:101], v[138:141], v[182:185], v[98:101]
	v_mfma_f32_16x16x32_bf16 v[126:129], v[134:137], v[150:153], v[126:129]
	v_mfma_f32_16x16x32_bf16 v[122:125], v[142:145], v[150:153], v[122:125]
	v_mfma_f32_16x16x32_bf16 v[118:121], v[134:137], v[170:173], v[118:121]
	v_mfma_f32_16x16x32_bf16 v[114:117], v[142:145], v[170:173], v[114:117]
	v_mfma_f32_16x16x32_bf16 v[110:113], v[134:137], v[178:181], v[110:113]
	v_mfma_f32_16x16x32_bf16 v[106:109], v[142:145], v[178:181], v[106:109]
	v_mfma_f32_16x16x32_bf16 v[102:105], v[134:137], v[186:189], v[102:105]
	v_mfma_f32_16x16x32_bf16 v[98:101], v[142:145], v[186:189], v[98:101]
	ds_read_b128 v[130:133], v191 offset:32768
	ds_read_b128 v[134:137], v191 offset:33792
	ds_read_b128 v[138:141], v191 offset:34816
	ds_read_b128 v[142:145], v191 offset:35840
	ds_read_b128 v[146:149], v190 offset:32768
	ds_read_b128 v[150:153], v190 offset:33792
	ds_read_b128 v[166:169], v190 offset:34816
	ds_read_b128 v[170:173], v190 offset:35840
	ds_read_b128 v[174:177], v190 offset:36864
	ds_read_b128 v[178:181], v190 offset:37888
	ds_read_b128 v[182:185], v190 offset:38912
	ds_read_b128 v[186:189], v190 offset:39936
	s_waitcnt lgkmcnt(0)
	s_waitcnt vmcnt(8)
	s_barrier
	s_add_i32 m0, s44, 0x8000
	s_nop 0
	global_load_lds_dwordx4 v250, s[0:1]
	s_add_i32 m0, s44, 0xa000
	s_nop 0
	global_load_lds_dwordx4 v251, s[0:1]
	s_add_i32 m0, s45, 0x8000
	s_nop 0
	global_load_lds_dwordx4 v0, s[16:17]
	s_add_i32 m0, s45, 0xa000
	s_nop 0
	global_load_lds_dwordx4 v154, s[16:17]
	s_add_u32 s0, s0, 0x80
	s_addc_u32 s1, s1, 0
	s_add_u32 s16, s16, 0x80
	s_addc_u32 s17, s17, 0
	v_mfma_f32_16x16x32_bf16 v[126:129], v[130:133], v[146:149], v[126:129]
	v_mfma_f32_16x16x32_bf16 v[122:125], v[138:141], v[146:149], v[122:125]
	v_mfma_f32_16x16x32_bf16 v[118:121], v[130:133], v[166:169], v[118:121]
	v_mfma_f32_16x16x32_bf16 v[114:117], v[138:141], v[166:169], v[114:117]
	v_mfma_f32_16x16x32_bf16 v[110:113], v[130:133], v[174:177], v[110:113]
	v_mfma_f32_16x16x32_bf16 v[106:109], v[138:141], v[174:177], v[106:109]
	v_mfma_f32_16x16x32_bf16 v[102:105], v[130:133], v[182:185], v[102:105]
	v_mfma_f32_16x16x32_bf16 v[98:101], v[138:141], v[182:185], v[98:101]
	v_mfma_f32_16x16x32_bf16 v[126:129], v[134:137], v[150:153], v[126:129]
	v_mfma_f32_16x16x32_bf16 v[122:125], v[142:145], v[150:153], v[122:125]
	v_mfma_f32_16x16x32_bf16 v[118:121], v[134:137], v[170:173], v[118:121]
	v_mfma_f32_16x16x32_bf16 v[114:117], v[142:145], v[170:173], v[114:117]
	v_mfma_f32_16x16x32_bf16 v[110:113], v[134:137], v[178:181], v[110:113]
	v_mfma_f32_16x16x32_bf16 v[106:109], v[142:145], v[178:181], v[106:109]
	v_mfma_f32_16x16x32_bf16 v[102:105], v[134:137], v[186:189], v[102:105]
	v_mfma_f32_16x16x32_bf16 v[98:101], v[142:145], v[186:189], v[98:101]
	ds_read_b128 v[130:133], v193 offset:0
	ds_read_b128 v[134:137], v193 offset:1024
	ds_read_b128 v[138:141], v193 offset:2048
	ds_read_b128 v[142:145], v193 offset:3072
	ds_read_b128 v[146:149], v192 offset:0
	ds_read_b128 v[150:153], v192 offset:1024
	ds_read_b128 v[166:169], v192 offset:2048
	ds_read_b128 v[170:173], v192 offset:3072
	ds_read_b128 v[174:177], v192 offset:4096
	ds_read_b128 v[178:181], v192 offset:5120
	ds_read_b128 v[182:185], v192 offset:6144
	ds_read_b128 v[186:189], v192 offset:7168
	s_waitcnt lgkmcnt(0)
	s_waitcnt vmcnt(8)
	s_barrier
	s_add_i32 m0, s46, 0x0
	s_nop 0
	global_load_lds_dwordx4 v250, s[0:1]
	s_add_i32 m0, s46, 0x2000
	s_nop 0
	global_load_lds_dwordx4 v251, s[0:1]
	s_add_i32 m0, s47, 0x0
	s_nop 0
	global_load_lds_dwordx4 v0, s[16:17]
	s_add_i32 m0, s47, 0x2000
	s_nop 0
	global_load_lds_dwordx4 v154, s[16:17]
	s_add_u32 s0, s0, 0x80
	s_addc_u32 s1, s1, 0
	s_add_u32 s16, s16, 0x80
	s_addc_u32 s17, s17, 0
	v_mfma_f32_16x16x32_bf16 v[126:129], v[130:133], v[146:149], v[126:129]
	v_mfma_f32_16x16x32_bf16 v[122:125], v[138:141], v[146:149], v[122:125]
	v_mfma_f32_16x16x32_bf16 v[118:121], v[130:133], v[166:169], v[118:121]
	v_mfma_f32_16x16x32_bf16 v[114:117], v[138:141], v[166:169], v[114:117]
	v_mfma_f32_16x16x32_bf16 v[110:113], v[130:133], v[174:177], v[110:113]
	v_mfma_f32_16x16x32_bf16 v[106:109], v[138:141], v[174:177], v[106:109]
	v_mfma_f32_16x16x32_bf16 v[102:105], v[130:133], v[182:185], v[102:105]
	v_mfma_f32_16x16x32_bf16 v[98:101], v[138:141], v[182:185], v[98:101]
	v_mfma_f32_16x16x32_bf16 v[126:129], v[134:137], v[150:153], v[126:129]
	v_mfma_f32_16x16x32_bf16 v[122:125], v[142:145], v[150:153], v[122:125]
	v_mfma_f32_16x16x32_bf16 v[118:121], v[134:137], v[170:173], v[118:121]
	v_mfma_f32_16x16x32_bf16 v[114:117], v[142:145], v[170:173], v[114:117]
	v_mfma_f32_16x16x32_bf16 v[110:113], v[134:137], v[178:181], v[110:113]
	v_mfma_f32_16x16x32_bf16 v[106:109], v[142:145], v[178:181], v[106:109]
	v_mfma_f32_16x16x32_bf16 v[102:105], v[134:137], v[186:189], v[102:105]
	v_mfma_f32_16x16x32_bf16 v[98:101], v[142:145], v[186:189], v[98:101]
	ds_read_b128 v[130:133], v193 offset:32768
	ds_read_b128 v[134:137], v193 offset:33792
	ds_read_b128 v[138:141], v193 offset:34816
	ds_read_b128 v[142:145], v193 offset:35840
	ds_read_b128 v[146:149], v192 offset:32768
	ds_read_b128 v[150:153], v192 offset:33792
	ds_read_b128 v[166:169], v192 offset:34816
	ds_read_b128 v[170:173], v192 offset:35840
	ds_read_b128 v[174:177], v192 offset:36864
	ds_read_b128 v[178:181], v192 offset:37888
	ds_read_b128 v[182:185], v192 offset:38912
	ds_read_b128 v[186:189], v192 offset:39936
	s_waitcnt lgkmcnt(0)
	s_waitcnt vmcnt(8)
	s_barrier
	s_add_i32 m0, s46, 0x8000
	s_nop 0
	global_load_lds_dwordx4 v250, s[0:1]
	s_add_i32 m0, s46, 0xa000
	s_nop 0
	global_load_lds_dwordx4 v251, s[0:1]
	s_add_i32 m0, s47, 0x8000
	s_nop 0
	global_load_lds_dwordx4 v0, s[16:17]
	s_add_i32 m0, s47, 0xa000
	s_nop 0
	global_load_lds_dwordx4 v154, s[16:17]
	s_add_u32 s0, s0, 0x80
	s_addc_u32 s1, s1, 0
	s_add_u32 s16, s16, 0x80
	s_addc_u32 s17, s17, 0
	v_mfma_f32_16x16x32_bf16 v[126:129], v[130:133], v[146:149], v[126:129]
	v_mfma_f32_16x16x32_bf16 v[122:125], v[138:141], v[146:149], v[122:125]
	v_mfma_f32_16x16x32_bf16 v[118:121], v[130:133], v[166:169], v[118:121]
	v_mfma_f32_16x16x32_bf16 v[114:117], v[138:141], v[166:169], v[114:117]
	v_mfma_f32_16x16x32_bf16 v[110:113], v[130:133], v[174:177], v[110:113]
	v_mfma_f32_16x16x32_bf16 v[106:109], v[138:141], v[174:177], v[106:109]
	v_mfma_f32_16x16x32_bf16 v[102:105], v[130:133], v[182:185], v[102:105]
	v_mfma_f32_16x16x32_bf16 v[98:101], v[138:141], v[182:185], v[98:101]
	v_mfma_f32_16x16x32_bf16 v[126:129], v[134:137], v[150:153], v[126:129]
	v_mfma_f32_16x16x32_bf16 v[122:125], v[142:145], v[150:153], v[122:125]
	v_mfma_f32_16x16x32_bf16 v[118:121], v[134:137], v[170:173], v[118:121]
	v_mfma_f32_16x16x32_bf16 v[114:117], v[142:145], v[170:173], v[114:117]
	v_mfma_f32_16x16x32_bf16 v[110:113], v[134:137], v[178:181], v[110:113]
	v_mfma_f32_16x16x32_bf16 v[106:109], v[142:145], v[178:181], v[106:109]
	v_mfma_f32_16x16x32_bf16 v[102:105], v[134:137], v[186:189], v[102:105]
	v_mfma_f32_16x16x32_bf16 v[98:101], v[142:145], v[186:189], v[98:101]
	ds_read_b128 v[130:133], v191 offset:0
	ds_read_b128 v[134:137], v191 offset:1024
	ds_read_b128 v[138:141], v191 offset:2048
	ds_read_b128 v[142:145], v191 offset:3072
	ds_read_b128 v[146:149], v190 offset:0
	ds_read_b128 v[150:153], v190 offset:1024
	ds_read_b128 v[166:169], v190 offset:2048
	ds_read_b128 v[170:173], v190 offset:3072
	ds_read_b128 v[174:177], v190 offset:4096
	ds_read_b128 v[178:181], v190 offset:5120
	ds_read_b128 v[182:185], v190 offset:6144
	ds_read_b128 v[186:189], v190 offset:7168
	s_waitcnt lgkmcnt(0)
	s_waitcnt vmcnt(8)
	s_barrier
	s_add_i32 m0, s44, 0x0
	s_nop 0
	global_load_lds_dwordx4 v250, s[0:1]
	s_add_i32 m0, s44, 0x2000
	s_nop 0
	global_load_lds_dwordx4 v251, s[0:1]
	s_add_i32 m0, s45, 0x0
	s_nop 0
	global_load_lds_dwordx4 v0, s[16:17]
	s_add_i32 m0, s45, 0x2000
	s_nop 0
	global_load_lds_dwordx4 v154, s[16:17]
	s_add_u32 s0, s0, 0x80
	s_addc_u32 s1, s1, 0
	s_add_u32 s16, s16, 0x80
	s_addc_u32 s17, s17, 0
	v_mfma_f32_16x16x32_bf16 v[126:129], v[130:133], v[146:149], v[126:129]
	v_mfma_f32_16x16x32_bf16 v[122:125], v[138:141], v[146:149], v[122:125]
	v_mfma_f32_16x16x32_bf16 v[118:121], v[130:133], v[166:169], v[118:121]
	v_mfma_f32_16x16x32_bf16 v[114:117], v[138:141], v[166:169], v[114:117]
	v_mfma_f32_16x16x32_bf16 v[110:113], v[130:133], v[174:177], v[110:113]
	v_mfma_f32_16x16x32_bf16 v[106:109], v[138:141], v[174:177], v[106:109]
	v_mfma_f32_16x16x32_bf16 v[102:105], v[130:133], v[182:185], v[102:105]
	v_mfma_f32_16x16x32_bf16 v[98:101], v[138:141], v[182:185], v[98:101]
	v_mfma_f32_16x16x32_bf16 v[126:129], v[134:137], v[150:153], v[126:129]
	v_mfma_f32_16x16x32_bf16 v[122:125], v[142:145], v[150:153], v[122:125]
	v_mfma_f32_16x16x32_bf16 v[118:121], v[134:137], v[170:173], v[118:121]
	v_mfma_f32_16x16x32_bf16 v[114:117], v[142:145], v[170:173], v[114:117]
	v_mfma_f32_16x16x32_bf16 v[110:113], v[134:137], v[178:181], v[110:113]
	v_mfma_f32_16x16x32_bf16 v[106:109], v[142:145], v[178:181], v[106:109]
	v_mfma_f32_16x16x32_bf16 v[102:105], v[134:137], v[186:189], v[102:105]
	v_mfma_f32_16x16x32_bf16 v[98:101], v[142:145], v[186:189], v[98:101]
	ds_read_b128 v[130:133], v191 offset:32768
	ds_read_b128 v[134:137], v191 offset:33792
	ds_read_b128 v[138:141], v191 offset:34816
	ds_read_b128 v[142:145], v191 offset:35840
	ds_read_b128 v[146:149], v190 offset:32768
	ds_read_b128 v[150:153], v190 offset:33792
	ds_read_b128 v[166:169], v190 offset:34816
	ds_read_b128 v[170:173], v190 offset:35840
	ds_read_b128 v[174:177], v190 offset:36864
	ds_read_b128 v[178:181], v190 offset:37888
	ds_read_b128 v[182:185], v190 offset:38912
	ds_read_b128 v[186:189], v190 offset:39936
	s_waitcnt lgkmcnt(0)
	s_waitcnt vmcnt(8)
	s_barrier
	s_add_i32 m0, s44, 0x8000
	s_nop 0
	global_load_lds_dwordx4 v250, s[0:1]
	s_add_i32 m0, s44, 0xa000
	s_nop 0
	global_load_lds_dwordx4 v251, s[0:1]
	s_add_i32 m0, s45, 0x8000
	s_nop 0
	global_load_lds_dwordx4 v0, s[16:17]
	s_add_i32 m0, s45, 0xa000
	s_nop 0
	global_load_lds_dwordx4 v154, s[16:17]
	s_add_u32 s0, s0, 0x80
	s_addc_u32 s1, s1, 0
	s_add_u32 s16, s16, 0x80
	s_addc_u32 s17, s17, 0
	v_mfma_f32_16x16x32_bf16 v[126:129], v[130:133], v[146:149], v[126:129]
	v_mfma_f32_16x16x32_bf16 v[122:125], v[138:141], v[146:149], v[122:125]
	v_mfma_f32_16x16x32_bf16 v[118:121], v[130:133], v[166:169], v[118:121]
	v_mfma_f32_16x16x32_bf16 v[114:117], v[138:141], v[166:169], v[114:117]
	v_mfma_f32_16x16x32_bf16 v[110:113], v[130:133], v[174:177], v[110:113]
	v_mfma_f32_16x16x32_bf16 v[106:109], v[138:141], v[174:177], v[106:109]
	v_mfma_f32_16x16x32_bf16 v[102:105], v[130:133], v[182:185], v[102:105]
	v_mfma_f32_16x16x32_bf16 v[98:101], v[138:141], v[182:185], v[98:101]
	v_mfma_f32_16x16x32_bf16 v[126:129], v[134:137], v[150:153], v[126:129]
	v_mfma_f32_16x16x32_bf16 v[122:125], v[142:145], v[150:153], v[122:125]
	v_mfma_f32_16x16x32_bf16 v[118:121], v[134:137], v[170:173], v[118:121]
	v_mfma_f32_16x16x32_bf16 v[114:117], v[142:145], v[170:173], v[114:117]
	v_mfma_f32_16x16x32_bf16 v[110:113], v[134:137], v[178:181], v[110:113]
	v_mfma_f32_16x16x32_bf16 v[106:109], v[142:145], v[178:181], v[106:109]
	v_mfma_f32_16x16x32_bf16 v[102:105], v[134:137], v[186:189], v[102:105]
	v_mfma_f32_16x16x32_bf16 v[98:101], v[142:145], v[186:189], v[98:101]
	ds_read_b128 v[130:133], v193 offset:0
	ds_read_b128 v[134:137], v193 offset:1024
	ds_read_b128 v[138:141], v193 offset:2048
	ds_read_b128 v[142:145], v193 offset:3072
	ds_read_b128 v[146:149], v192 offset:0
	ds_read_b128 v[150:153], v192 offset:1024
	ds_read_b128 v[166:169], v192 offset:2048
	ds_read_b128 v[170:173], v192 offset:3072
	ds_read_b128 v[174:177], v192 offset:4096
	ds_read_b128 v[178:181], v192 offset:5120
	ds_read_b128 v[182:185], v192 offset:6144
	ds_read_b128 v[186:189], v192 offset:7168
	s_waitcnt lgkmcnt(0)
	s_waitcnt vmcnt(8)
	s_barrier
	s_add_i32 m0, s46, 0x0
	s_nop 0
	global_load_lds_dwordx4 v250, s[0:1]
	s_add_i32 m0, s46, 0x2000
	s_nop 0
	global_load_lds_dwordx4 v251, s[0:1]
	s_add_i32 m0, s47, 0x0
	s_nop 0
	global_load_lds_dwordx4 v0, s[16:17]
	s_add_i32 m0, s47, 0x2000
	s_nop 0
	global_load_lds_dwordx4 v154, s[16:17]
	s_add_u32 s0, s0, 0x80
	s_addc_u32 s1, s1, 0
	s_add_u32 s16, s16, 0x80
	s_addc_u32 s17, s17, 0
	v_mfma_f32_16x16x32_bf16 v[126:129], v[130:133], v[146:149], v[126:129]
	v_mfma_f32_16x16x32_bf16 v[122:125], v[138:141], v[146:149], v[122:125]
	v_mfma_f32_16x16x32_bf16 v[118:121], v[130:133], v[166:169], v[118:121]
	v_mfma_f32_16x16x32_bf16 v[114:117], v[138:141], v[166:169], v[114:117]
	v_mfma_f32_16x16x32_bf16 v[110:113], v[130:133], v[174:177], v[110:113]
	v_mfma_f32_16x16x32_bf16 v[106:109], v[138:141], v[174:177], v[106:109]
	v_mfma_f32_16x16x32_bf16 v[102:105], v[130:133], v[182:185], v[102:105]
	v_mfma_f32_16x16x32_bf16 v[98:101], v[138:141], v[182:185], v[98:101]
	v_mfma_f32_16x16x32_bf16 v[126:129], v[134:137], v[150:153], v[126:129]
	v_mfma_f32_16x16x32_bf16 v[122:125], v[142:145], v[150:153], v[122:125]
	v_mfma_f32_16x16x32_bf16 v[118:121], v[134:137], v[170:173], v[118:121]
	v_mfma_f32_16x16x32_bf16 v[114:117], v[142:145], v[170:173], v[114:117]
	v_mfma_f32_16x16x32_bf16 v[110:113], v[134:137], v[178:181], v[110:113]
	v_mfma_f32_16x16x32_bf16 v[106:109], v[142:145], v[178:181], v[106:109]
	v_mfma_f32_16x16x32_bf16 v[102:105], v[134:137], v[186:189], v[102:105]
	v_mfma_f32_16x16x32_bf16 v[98:101], v[142:145], v[186:189], v[98:101]
	ds_read_b128 v[130:133], v193 offset:32768
	ds_read_b128 v[134:137], v193 offset:33792
	ds_read_b128 v[138:141], v193 offset:34816
	ds_read_b128 v[142:145], v193 offset:35840
	ds_read_b128 v[146:149], v192 offset:32768
	ds_read_b128 v[150:153], v192 offset:33792
	ds_read_b128 v[166:169], v192 offset:34816
	ds_read_b128 v[170:173], v192 offset:35840
	ds_read_b128 v[174:177], v192 offset:36864
	ds_read_b128 v[178:181], v192 offset:37888
	ds_read_b128 v[182:185], v192 offset:38912
	ds_read_b128 v[186:189], v192 offset:39936
	s_waitcnt lgkmcnt(0)
	s_waitcnt vmcnt(8)
	s_barrier
	s_add_i32 m0, s46, 0x8000
	s_nop 0
	global_load_lds_dwordx4 v250, s[0:1]
	s_add_i32 m0, s46, 0xa000
	s_nop 0
	global_load_lds_dwordx4 v251, s[0:1]
	s_add_i32 m0, s47, 0x8000
	s_nop 0
	global_load_lds_dwordx4 v0, s[16:17]
	s_add_i32 m0, s47, 0xa000
	s_nop 0
	global_load_lds_dwordx4 v154, s[16:17]
	s_add_u32 s0, s0, 0x80
	s_addc_u32 s1, s1, 0
	s_add_u32 s16, s16, 0x80
	s_addc_u32 s17, s17, 0
	v_mfma_f32_16x16x32_bf16 v[126:129], v[130:133], v[146:149], v[126:129]
	v_mfma_f32_16x16x32_bf16 v[122:125], v[138:141], v[146:149], v[122:125]
	v_mfma_f32_16x16x32_bf16 v[118:121], v[130:133], v[166:169], v[118:121]
	v_mfma_f32_16x16x32_bf16 v[114:117], v[138:141], v[166:169], v[114:117]
	v_mfma_f32_16x16x32_bf16 v[110:113], v[130:133], v[174:177], v[110:113]
	v_mfma_f32_16x16x32_bf16 v[106:109], v[138:141], v[174:177], v[106:109]
	v_mfma_f32_16x16x32_bf16 v[102:105], v[130:133], v[182:185], v[102:105]
	v_mfma_f32_16x16x32_bf16 v[98:101], v[138:141], v[182:185], v[98:101]
	v_mfma_f32_16x16x32_bf16 v[126:129], v[134:137], v[150:153], v[126:129]
	v_mfma_f32_16x16x32_bf16 v[122:125], v[142:145], v[150:153], v[122:125]
	v_mfma_f32_16x16x32_bf16 v[118:121], v[134:137], v[170:173], v[118:121]
	v_mfma_f32_16x16x32_bf16 v[114:117], v[142:145], v[170:173], v[114:117]
	v_mfma_f32_16x16x32_bf16 v[110:113], v[134:137], v[178:181], v[110:113]
	v_mfma_f32_16x16x32_bf16 v[106:109], v[142:145], v[178:181], v[106:109]
	v_mfma_f32_16x16x32_bf16 v[102:105], v[134:137], v[186:189], v[102:105]
	v_mfma_f32_16x16x32_bf16 v[98:101], v[142:145], v[186:189], v[98:101]
	ds_read_b128 v[130:133], v191 offset:0
	ds_read_b128 v[134:137], v191 offset:1024
	ds_read_b128 v[138:141], v191 offset:2048
	ds_read_b128 v[142:145], v191 offset:3072
	ds_read_b128 v[146:149], v190 offset:0
	ds_read_b128 v[150:153], v190 offset:1024
	ds_read_b128 v[166:169], v190 offset:2048
	ds_read_b128 v[170:173], v190 offset:3072
	ds_read_b128 v[174:177], v190 offset:4096
	ds_read_b128 v[178:181], v190 offset:5120
	ds_read_b128 v[182:185], v190 offset:6144
	ds_read_b128 v[186:189], v190 offset:7168
	s_waitcnt lgkmcnt(0)
	s_waitcnt vmcnt(8)
	s_barrier
	s_add_i32 m0, s44, 0x0
	s_nop 0
	global_load_lds_dwordx4 v250, s[0:1]
	s_add_i32 m0, s44, 0x2000
	s_nop 0
	global_load_lds_dwordx4 v251, s[0:1]
	s_add_i32 m0, s45, 0x0
	s_nop 0
	global_load_lds_dwordx4 v0, s[16:17]
	s_add_i32 m0, s45, 0x2000
	s_nop 0
	global_load_lds_dwordx4 v154, s[16:17]
	s_add_u32 s0, s0, 0x80
	s_addc_u32 s1, s1, 0
	s_add_u32 s16, s16, 0x80
	s_addc_u32 s17, s17, 0
	v_mfma_f32_16x16x32_bf16 v[126:129], v[130:133], v[146:149], v[126:129]
	v_mfma_f32_16x16x32_bf16 v[122:125], v[138:141], v[146:149], v[122:125]
	v_mfma_f32_16x16x32_bf16 v[118:121], v[130:133], v[166:169], v[118:121]
	v_mfma_f32_16x16x32_bf16 v[114:117], v[138:141], v[166:169], v[114:117]
	v_mfma_f32_16x16x32_bf16 v[110:113], v[130:133], v[174:177], v[110:113]
	v_mfma_f32_16x16x32_bf16 v[106:109], v[138:141], v[174:177], v[106:109]
	v_mfma_f32_16x16x32_bf16 v[102:105], v[130:133], v[182:185], v[102:105]
	v_mfma_f32_16x16x32_bf16 v[98:101], v[138:141], v[182:185], v[98:101]
	v_mfma_f32_16x16x32_bf16 v[126:129], v[134:137], v[150:153], v[126:129]
	v_mfma_f32_16x16x32_bf16 v[122:125], v[142:145], v[150:153], v[122:125]
	v_mfma_f32_16x16x32_bf16 v[118:121], v[134:137], v[170:173], v[118:121]
	v_mfma_f32_16x16x32_bf16 v[114:117], v[142:145], v[170:173], v[114:117]
	v_mfma_f32_16x16x32_bf16 v[110:113], v[134:137], v[178:181], v[110:113]
	v_mfma_f32_16x16x32_bf16 v[106:109], v[142:145], v[178:181], v[106:109]
	v_mfma_f32_16x16x32_bf16 v[102:105], v[134:137], v[186:189], v[102:105]
	v_mfma_f32_16x16x32_bf16 v[98:101], v[142:145], v[186:189], v[98:101]
	ds_read_b128 v[130:133], v191 offset:32768
	ds_read_b128 v[134:137], v191 offset:33792
	ds_read_b128 v[138:141], v191 offset:34816
	ds_read_b128 v[142:145], v191 offset:35840
	ds_read_b128 v[146:149], v190 offset:32768
	ds_read_b128 v[150:153], v190 offset:33792
	ds_read_b128 v[166:169], v190 offset:34816
	ds_read_b128 v[170:173], v190 offset:35840
	ds_read_b128 v[174:177], v190 offset:36864
	ds_read_b128 v[178:181], v190 offset:37888
	ds_read_b128 v[182:185], v190 offset:38912
	ds_read_b128 v[186:189], v190 offset:39936
	s_waitcnt lgkmcnt(0)
	s_waitcnt vmcnt(8)
	s_barrier
	s_add_i32 m0, s44, 0x8000
	s_nop 0
	global_load_lds_dwordx4 v250, s[0:1]
	s_add_i32 m0, s44, 0xa000
	s_nop 0
	global_load_lds_dwordx4 v251, s[0:1]
	s_add_i32 m0, s45, 0x8000
	s_nop 0
	global_load_lds_dwordx4 v0, s[16:17]
	s_add_i32 m0, s45, 0xa000
	s_nop 0
	global_load_lds_dwordx4 v154, s[16:17]
	s_add_u32 s0, s0, 0x80
	s_addc_u32 s1, s1, 0
	s_add_u32 s16, s16, 0x80
	s_addc_u32 s17, s17, 0
	v_mfma_f32_16x16x32_bf16 v[126:129], v[130:133], v[146:149], v[126:129]
	v_mfma_f32_16x16x32_bf16 v[122:125], v[138:141], v[146:149], v[122:125]
	v_mfma_f32_16x16x32_bf16 v[118:121], v[130:133], v[166:169], v[118:121]
	v_mfma_f32_16x16x32_bf16 v[114:117], v[138:141], v[166:169], v[114:117]
	v_mfma_f32_16x16x32_bf16 v[110:113], v[130:133], v[174:177], v[110:113]
	v_mfma_f32_16x16x32_bf16 v[106:109], v[138:141], v[174:177], v[106:109]
	v_mfma_f32_16x16x32_bf16 v[102:105], v[130:133], v[182:185], v[102:105]
	v_mfma_f32_16x16x32_bf16 v[98:101], v[138:141], v[182:185], v[98:101]
	v_mfma_f32_16x16x32_bf16 v[126:129], v[134:137], v[150:153], v[126:129]
	v_mfma_f32_16x16x32_bf16 v[122:125], v[142:145], v[150:153], v[122:125]
	v_mfma_f32_16x16x32_bf16 v[118:121], v[134:137], v[170:173], v[118:121]
	v_mfma_f32_16x16x32_bf16 v[114:117], v[142:145], v[170:173], v[114:117]
	v_mfma_f32_16x16x32_bf16 v[110:113], v[134:137], v[178:181], v[110:113]
	v_mfma_f32_16x16x32_bf16 v[106:109], v[142:145], v[178:181], v[106:109]
	v_mfma_f32_16x16x32_bf16 v[102:105], v[134:137], v[186:189], v[102:105]
	v_mfma_f32_16x16x32_bf16 v[98:101], v[142:145], v[186:189], v[98:101]
	ds_read_b128 v[130:133], v193 offset:0
	ds_read_b128 v[134:137], v193 offset:1024
	ds_read_b128 v[138:141], v193 offset:2048
	ds_read_b128 v[142:145], v193 offset:3072
	ds_read_b128 v[146:149], v192 offset:0
	ds_read_b128 v[150:153], v192 offset:1024
	ds_read_b128 v[166:169], v192 offset:2048
	ds_read_b128 v[170:173], v192 offset:3072
	ds_read_b128 v[174:177], v192 offset:4096
	ds_read_b128 v[178:181], v192 offset:5120
	ds_read_b128 v[182:185], v192 offset:6144
	ds_read_b128 v[186:189], v192 offset:7168
	s_waitcnt lgkmcnt(0)
	s_waitcnt vmcnt(8)
	s_barrier
	s_add_i32 m0, s46, 0x0
	s_nop 0
	global_load_lds_dwordx4 v250, s[0:1]
	s_add_i32 m0, s46, 0x2000
	s_nop 0
	global_load_lds_dwordx4 v251, s[0:1]
	s_add_i32 m0, s47, 0x0
	s_nop 0
	global_load_lds_dwordx4 v0, s[16:17]
	s_add_i32 m0, s47, 0x2000
	s_nop 0
	global_load_lds_dwordx4 v154, s[16:17]
	s_add_u32 s0, s0, 0x80
	s_addc_u32 s1, s1, 0
	s_add_u32 s16, s16, 0x80
	s_addc_u32 s17, s17, 0
	v_mfma_f32_16x16x32_bf16 v[126:129], v[130:133], v[146:149], v[126:129]
	v_mfma_f32_16x16x32_bf16 v[122:125], v[138:141], v[146:149], v[122:125]
	v_mfma_f32_16x16x32_bf16 v[118:121], v[130:133], v[166:169], v[118:121]
	v_mfma_f32_16x16x32_bf16 v[114:117], v[138:141], v[166:169], v[114:117]
	v_mfma_f32_16x16x32_bf16 v[110:113], v[130:133], v[174:177], v[110:113]
	v_mfma_f32_16x16x32_bf16 v[106:109], v[138:141], v[174:177], v[106:109]
	v_mfma_f32_16x16x32_bf16 v[102:105], v[130:133], v[182:185], v[102:105]
	v_mfma_f32_16x16x32_bf16 v[98:101], v[138:141], v[182:185], v[98:101]
	v_mfma_f32_16x16x32_bf16 v[126:129], v[134:137], v[150:153], v[126:129]
	v_mfma_f32_16x16x32_bf16 v[122:125], v[142:145], v[150:153], v[122:125]
	v_mfma_f32_16x16x32_bf16 v[118:121], v[134:137], v[170:173], v[118:121]
	v_mfma_f32_16x16x32_bf16 v[114:117], v[142:145], v[170:173], v[114:117]
	v_mfma_f32_16x16x32_bf16 v[110:113], v[134:137], v[178:181], v[110:113]
	v_mfma_f32_16x16x32_bf16 v[106:109], v[142:145], v[178:181], v[106:109]
	v_mfma_f32_16x16x32_bf16 v[102:105], v[134:137], v[186:189], v[102:105]
	v_mfma_f32_16x16x32_bf16 v[98:101], v[142:145], v[186:189], v[98:101]
	ds_read_b128 v[130:133], v193 offset:32768
	ds_read_b128 v[134:137], v193 offset:33792
	ds_read_b128 v[138:141], v193 offset:34816
	ds_read_b128 v[142:145], v193 offset:35840
	ds_read_b128 v[146:149], v192 offset:32768
	ds_read_b128 v[150:153], v192 offset:33792
	ds_read_b128 v[166:169], v192 offset:34816
	ds_read_b128 v[170:173], v192 offset:35840
	ds_read_b128 v[174:177], v192 offset:36864
	ds_read_b128 v[178:181], v192 offset:37888
	ds_read_b128 v[182:185], v192 offset:38912
	ds_read_b128 v[186:189], v192 offset:39936
	s_waitcnt lgkmcnt(0)
	s_waitcnt vmcnt(8)
	s_barrier
	s_add_i32 m0, s46, 0x8000
	s_nop 0
	global_load_lds_dwordx4 v250, s[0:1]
	s_add_i32 m0, s46, 0xa000
	s_nop 0
	global_load_lds_dwordx4 v251, s[0:1]
	s_add_i32 m0, s47, 0x8000
	s_nop 0
	global_load_lds_dwordx4 v0, s[16:17]
	s_add_i32 m0, s47, 0xa000
	s_nop 0
	global_load_lds_dwordx4 v154, s[16:17]
	s_add_u32 s0, s0, 0x80
	s_addc_u32 s1, s1, 0
	s_add_u32 s16, s16, 0x80
	s_addc_u32 s17, s17, 0
	v_mfma_f32_16x16x32_bf16 v[126:129], v[130:133], v[146:149], v[126:129]
	v_mfma_f32_16x16x32_bf16 v[122:125], v[138:141], v[146:149], v[122:125]
	v_mfma_f32_16x16x32_bf16 v[118:121], v[130:133], v[166:169], v[118:121]
	v_mfma_f32_16x16x32_bf16 v[114:117], v[138:141], v[166:169], v[114:117]
	v_mfma_f32_16x16x32_bf16 v[110:113], v[130:133], v[174:177], v[110:113]
	v_mfma_f32_16x16x32_bf16 v[106:109], v[138:141], v[174:177], v[106:109]
	v_mfma_f32_16x16x32_bf16 v[102:105], v[130:133], v[182:185], v[102:105]
	v_mfma_f32_16x16x32_bf16 v[98:101], v[138:141], v[182:185], v[98:101]
	v_mfma_f32_16x16x32_bf16 v[126:129], v[134:137], v[150:153], v[126:129]
	v_mfma_f32_16x16x32_bf16 v[122:125], v[142:145], v[150:153], v[122:125]
	v_mfma_f32_16x16x32_bf16 v[118:121], v[134:137], v[170:173], v[118:121]
	v_mfma_f32_16x16x32_bf16 v[114:117], v[142:145], v[170:173], v[114:117]
	v_mfma_f32_16x16x32_bf16 v[110:113], v[134:137], v[178:181], v[110:113]
	v_mfma_f32_16x16x32_bf16 v[106:109], v[142:145], v[178:181], v[106:109]
	v_mfma_f32_16x16x32_bf16 v[102:105], v[134:137], v[186:189], v[102:105]
	v_mfma_f32_16x16x32_bf16 v[98:101], v[142:145], v[186:189], v[98:101]
	ds_read_b128 v[130:133], v191 offset:0
	ds_read_b128 v[134:137], v191 offset:1024
	ds_read_b128 v[138:141], v191 offset:2048
	ds_read_b128 v[142:145], v191 offset:3072
	ds_read_b128 v[146:149], v190 offset:0
	ds_read_b128 v[150:153], v190 offset:1024
	ds_read_b128 v[166:169], v190 offset:2048
	ds_read_b128 v[170:173], v190 offset:3072
	ds_read_b128 v[174:177], v190 offset:4096
	ds_read_b128 v[178:181], v190 offset:5120
	ds_read_b128 v[182:185], v190 offset:6144
	ds_read_b128 v[186:189], v190 offset:7168
	s_waitcnt lgkmcnt(0)
	s_waitcnt vmcnt(8)
	s_barrier
	v_mfma_f32_16x16x32_bf16 v[126:129], v[130:133], v[146:149], v[126:129]
	v_mfma_f32_16x16x32_bf16 v[122:125], v[138:141], v[146:149], v[122:125]
	v_mfma_f32_16x16x32_bf16 v[118:121], v[130:133], v[166:169], v[118:121]
	v_mfma_f32_16x16x32_bf16 v[114:117], v[138:141], v[166:169], v[114:117]
	v_mfma_f32_16x16x32_bf16 v[110:113], v[130:133], v[174:177], v[110:113]
	v_mfma_f32_16x16x32_bf16 v[106:109], v[138:141], v[174:177], v[106:109]
	v_mfma_f32_16x16x32_bf16 v[102:105], v[130:133], v[182:185], v[102:105]
	v_mfma_f32_16x16x32_bf16 v[98:101], v[138:141], v[182:185], v[98:101]
	v_mfma_f32_16x16x32_bf16 v[126:129], v[134:137], v[150:153], v[126:129]
	v_mfma_f32_16x16x32_bf16 v[122:125], v[142:145], v[150:153], v[122:125]
	v_mfma_f32_16x16x32_bf16 v[118:121], v[134:137], v[170:173], v[118:121]
	v_mfma_f32_16x16x32_bf16 v[114:117], v[142:145], v[170:173], v[114:117]
	v_mfma_f32_16x16x32_bf16 v[110:113], v[134:137], v[178:181], v[110:113]
	v_mfma_f32_16x16x32_bf16 v[106:109], v[142:145], v[178:181], v[106:109]
	v_mfma_f32_16x16x32_bf16 v[102:105], v[134:137], v[186:189], v[102:105]
	v_mfma_f32_16x16x32_bf16 v[98:101], v[142:145], v[186:189], v[98:101]
	ds_read_b128 v[130:133], v191 offset:32768
	ds_read_b128 v[134:137], v191 offset:33792
	ds_read_b128 v[138:141], v191 offset:34816
	ds_read_b128 v[142:145], v191 offset:35840
	ds_read_b128 v[146:149], v190 offset:32768
	ds_read_b128 v[150:153], v190 offset:33792
	ds_read_b128 v[166:169], v190 offset:34816
	ds_read_b128 v[170:173], v190 offset:35840
	ds_read_b128 v[174:177], v190 offset:36864
	ds_read_b128 v[178:181], v190 offset:37888
	ds_read_b128 v[182:185], v190 offset:38912
	ds_read_b128 v[186:189], v190 offset:39936
	s_waitcnt lgkmcnt(0)
	s_waitcnt vmcnt(4)
	s_barrier
	v_mfma_f32_16x16x32_bf16 v[126:129], v[130:133], v[146:149], v[126:129]
	v_mfma_f32_16x16x32_bf16 v[122:125], v[138:141], v[146:149], v[122:125]
	v_mfma_f32_16x16x32_bf16 v[118:121], v[130:133], v[166:169], v[118:121]
	v_mfma_f32_16x16x32_bf16 v[114:117], v[138:141], v[166:169], v[114:117]
	v_mfma_f32_16x16x32_bf16 v[110:113], v[130:133], v[174:177], v[110:113]
	v_mfma_f32_16x16x32_bf16 v[106:109], v[138:141], v[174:177], v[106:109]
	v_mfma_f32_16x16x32_bf16 v[102:105], v[130:133], v[182:185], v[102:105]
	v_mfma_f32_16x16x32_bf16 v[98:101], v[138:141], v[182:185], v[98:101]
	v_mfma_f32_16x16x32_bf16 v[126:129], v[134:137], v[150:153], v[126:129]
	v_mfma_f32_16x16x32_bf16 v[122:125], v[142:145], v[150:153], v[122:125]
	v_mfma_f32_16x16x32_bf16 v[118:121], v[134:137], v[170:173], v[118:121]
	v_mfma_f32_16x16x32_bf16 v[114:117], v[142:145], v[170:173], v[114:117]
	v_mfma_f32_16x16x32_bf16 v[110:113], v[134:137], v[178:181], v[110:113]
	v_mfma_f32_16x16x32_bf16 v[106:109], v[142:145], v[178:181], v[106:109]
	v_mfma_f32_16x16x32_bf16 v[102:105], v[134:137], v[186:189], v[102:105]
	v_mfma_f32_16x16x32_bf16 v[98:101], v[142:145], v[186:189], v[98:101]
	ds_read_b128 v[130:133], v193 offset:0
	ds_read_b128 v[134:137], v193 offset:1024
	ds_read_b128 v[138:141], v193 offset:2048
	ds_read_b128 v[142:145], v193 offset:3072
	ds_read_b128 v[146:149], v192 offset:0
	ds_read_b128 v[150:153], v192 offset:1024
	ds_read_b128 v[166:169], v192 offset:2048
	ds_read_b128 v[170:173], v192 offset:3072
	ds_read_b128 v[174:177], v192 offset:4096
	ds_read_b128 v[178:181], v192 offset:5120
	ds_read_b128 v[182:185], v192 offset:6144
	ds_read_b128 v[186:189], v192 offset:7168
	s_waitcnt lgkmcnt(0)
	s_waitcnt vmcnt(0)
	s_barrier
	v_mfma_f32_16x16x32_bf16 v[126:129], v[130:133], v[146:149], v[126:129]
	v_mfma_f32_16x16x32_bf16 v[122:125], v[138:141], v[146:149], v[122:125]
	v_mfma_f32_16x16x32_bf16 v[118:121], v[130:133], v[166:169], v[118:121]
	v_mfma_f32_16x16x32_bf16 v[114:117], v[138:141], v[166:169], v[114:117]
	v_mfma_f32_16x16x32_bf16 v[110:113], v[130:133], v[174:177], v[110:113]
	v_mfma_f32_16x16x32_bf16 v[106:109], v[138:141], v[174:177], v[106:109]
	v_mfma_f32_16x16x32_bf16 v[102:105], v[130:133], v[182:185], v[102:105]
	v_mfma_f32_16x16x32_bf16 v[98:101], v[138:141], v[182:185], v[98:101]
	v_mfma_f32_16x16x32_bf16 v[126:129], v[134:137], v[150:153], v[126:129]
	v_mfma_f32_16x16x32_bf16 v[122:125], v[142:145], v[150:153], v[122:125]
	v_mfma_f32_16x16x32_bf16 v[118:121], v[134:137], v[170:173], v[118:121]
	v_mfma_f32_16x16x32_bf16 v[114:117], v[142:145], v[170:173], v[114:117]
	v_mfma_f32_16x16x32_bf16 v[110:113], v[134:137], v[178:181], v[110:113]
	v_mfma_f32_16x16x32_bf16 v[106:109], v[142:145], v[178:181], v[106:109]
	v_mfma_f32_16x16x32_bf16 v[102:105], v[134:137], v[186:189], v[102:105]
	v_mfma_f32_16x16x32_bf16 v[98:101], v[142:145], v[186:189], v[98:101]
	ds_read_b128 v[130:133], v193 offset:32768
	ds_read_b128 v[134:137], v193 offset:33792
	ds_read_b128 v[138:141], v193 offset:34816
	ds_read_b128 v[142:145], v193 offset:35840
	ds_read_b128 v[146:149], v192 offset:32768
	ds_read_b128 v[150:153], v192 offset:33792
	ds_read_b128 v[166:169], v192 offset:34816
	ds_read_b128 v[170:173], v192 offset:35840
	ds_read_b128 v[174:177], v192 offset:36864
	ds_read_b128 v[178:181], v192 offset:37888
	ds_read_b128 v[182:185], v192 offset:38912
	ds_read_b128 v[186:189], v192 offset:39936
	s_waitcnt lgkmcnt(0)
	v_mfma_f32_16x16x32_bf16 v[126:129], v[130:133], v[146:149], v[126:129]
	v_mfma_f32_16x16x32_bf16 v[122:125], v[138:141], v[146:149], v[122:125]
	v_mfma_f32_16x16x32_bf16 v[118:121], v[130:133], v[166:169], v[118:121]
	v_mfma_f32_16x16x32_bf16 v[114:117], v[138:141], v[166:169], v[114:117]
	v_mfma_f32_16x16x32_bf16 v[110:113], v[130:133], v[174:177], v[110:113]
	v_mfma_f32_16x16x32_bf16 v[106:109], v[138:141], v[174:177], v[106:109]
	v_mfma_f32_16x16x32_bf16 v[102:105], v[130:133], v[182:185], v[102:105]
	v_mfma_f32_16x16x32_bf16 v[98:101], v[138:141], v[182:185], v[98:101]
	v_mfma_f32_16x16x32_bf16 v[126:129], v[134:137], v[150:153], v[126:129]
	v_mfma_f32_16x16x32_bf16 v[122:125], v[142:145], v[150:153], v[122:125]
	v_mfma_f32_16x16x32_bf16 v[118:121], v[134:137], v[170:173], v[118:121]
	v_mfma_f32_16x16x32_bf16 v[114:117], v[142:145], v[170:173], v[114:117]
	v_mfma_f32_16x16x32_bf16 v[110:113], v[134:137], v[178:181], v[110:113]
	v_mfma_f32_16x16x32_bf16 v[106:109], v[142:145], v[178:181], v[106:109]
	v_mfma_f32_16x16x32_bf16 v[102:105], v[134:137], v[186:189], v[102:105]
	v_mfma_f32_16x16x32_bf16 v[98:101], v[142:145], v[186:189], v[98:101]
	s_nop 7
	s_nop 7
	s_bitcmp1_b32 s98, 0
	s_cbranch_scc1 .Lq_epi
	s_bitcmp1_b32 s98, 1
	s_cbranch_scc0 .Lq_mv1
	v_mov_b32_e32 v34, v98
	v_mov_b32_e32 v35, v99
	v_mov_b32_e32 v36, v100
	v_mov_b32_e32 v37, v101
	v_mov_b32_e32 v38, v102
	v_mov_b32_e32 v39, v103
	v_mov_b32_e32 v40, v104
	v_mov_b32_e32 v41, v105
	v_mov_b32_e32 v42, v106
	v_mov_b32_e32 v43, v107
	v_mov_b32_e32 v44, v108
	v_mov_b32_e32 v45, v109
	v_mov_b32_e32 v46, v110
	v_mov_b32_e32 v47, v111
	v_mov_b32_e32 v48, v112
	v_mov_b32_e32 v49, v113
	v_mov_b32_e32 v50, v114
	v_mov_b32_e32 v51, v115
	v_mov_b32_e32 v52, v116
	v_mov_b32_e32 v53, v117
	v_mov_b32_e32 v54, v118
	v_mov_b32_e32 v55, v119
	v_mov_b32_e32 v56, v120
	v_mov_b32_e32 v57, v121
	v_mov_b32_e32 v58, v122
	v_mov_b32_e32 v59, v123
	v_mov_b32_e32 v60, v124
	v_mov_b32_e32 v61, v125
	v_mov_b32_e32 v62, v126
	v_mov_b32_e32 v63, v127
	v_mov_b32_e32 v64, v128
	v_mov_b32_e32 v65, v129
	v_mov_b32_e32 v98, 0
	v_mov_b32_e32 v99, 0
	v_mov_b32_e32 v100, 0
	v_mov_b32_e32 v101, 0
	v_mov_b32_e32 v102, 0
	v_mov_b32_e32 v103, 0
	v_mov_b32_e32 v104, 0
	v_mov_b32_e32 v105, 0
	v_mov_b32_e32 v106, 0
	v_mov_b32_e32 v107, 0
	v_mov_b32_e32 v108, 0
	v_mov_b32_e32 v109, 0
	v_mov_b32_e32 v110, 0
	v_mov_b32_e32 v111, 0
	v_mov_b32_e32 v112, 0
	v_mov_b32_e32 v113, 0
	v_mov_b32_e32 v114, 0
	v_mov_b32_e32 v115, 0
	v_mov_b32_e32 v116, 0
	v_mov_b32_e32 v117, 0
	v_mov_b32_e32 v118, 0
	v_mov_b32_e32 v119, 0
	v_mov_b32_e32 v120, 0
	v_mov_b32_e32 v121, 0
	v_mov_b32_e32 v122, 0
	v_mov_b32_e32 v123, 0
	v_mov_b32_e32 v124, 0
	v_mov_b32_e32 v125, 0
	v_mov_b32_e32 v126, 0
	v_mov_b32_e32 v127, 0
	v_mov_b32_e32 v128, 0
	v_mov_b32_e32 v129, 0
	s_branch .Lq_epi
.Lq_mv1:
	s_bitcmp1_b32 s98, 2
	s_cbranch_scc0 .Lq_mv2
	v_mov_b32_e32 v66, v98
	v_mov_b32_e32 v67, v99
	v_mov_b32_e32 v68, v100
	v_mov_b32_e32 v69, v101
	v_mov_b32_e32 v70, v102
	v_mov_b32_e32 v71, v103
	v_mov_b32_e32 v72, v104
	v_mov_b32_e32 v73, v105
	v_mov_b32_e32 v74, v106
	v_mov_b32_e32 v75, v107
	v_mov_b32_e32 v76, v108
	v_mov_b32_e32 v77, v109
	v_mov_b32_e32 v78, v110
	v_mov_b32_e32 v79, v111
	v_mov_b32_e32 v80, v112
	v_mov_b32_e32 v81, v113
	v_mov_b32_e32 v82, v114
	v_mov_b32_e32 v83, v115
	v_mov_b32_e32 v84, v116
	v_mov_b32_e32 v85, v117
	v_mov_b32_e32 v86, v118
	v_mov_b32_e32 v87, v119
	v_mov_b32_e32 v88, v120
	v_mov_b32_e32 v89, v121
	v_mov_b32_e32 v90, v122
	v_mov_b32_e32 v91, v123
	v_mov_b32_e32 v92, v124
	v_mov_b32_e32 v93, v125
	v_mov_b32_e32 v94, v126
	v_mov_b32_e32 v95, v127
	v_mov_b32_e32 v96, v128
	v_mov_b32_e32 v97, v129
	v_mov_b32_e32 v98, 0
	v_mov_b32_e32 v99, 0
	v_mov_b32_e32 v100, 0
	v_mov_b32_e32 v101, 0
	v_mov_b32_e32 v102, 0
	v_mov_b32_e32 v103, 0
	v_mov_b32_e32 v104, 0
	v_mov_b32_e32 v105, 0
	v_mov_b32_e32 v106, 0
	v_mov_b32_e32 v107, 0
	v_mov_b32_e32 v108, 0
	v_mov_b32_e32 v109, 0
	v_mov_b32_e32 v110, 0
	v_mov_b32_e32 v111, 0
	v_mov_b32_e32 v112, 0
	v_mov_b32_e32 v113, 0
	v_mov_b32_e32 v114, 0
	v_mov_b32_e32 v115, 0
	v_mov_b32_e32 v116, 0
	v_mov_b32_e32 v117, 0
	v_mov_b32_e32 v118, 0
	v_mov_b32_e32 v119, 0
	v_mov_b32_e32 v120, 0
	v_mov_b32_e32 v121, 0
	v_mov_b32_e32 v122, 0
	v_mov_b32_e32 v123, 0
	v_mov_b32_e32 v124, 0
	v_mov_b32_e32 v125, 0
	v_mov_b32_e32 v126, 0
	v_mov_b32_e32 v127, 0
	v_mov_b32_e32 v128, 0
	v_mov_b32_e32 v129, 0
	s_branch .Lq_epi
.Lq_mv2:
	s_bitcmp1_b32 s98, 3
	s_cbranch_scc0 .Lq_mv3
	v_mov_b32_e32 v2, v98
	v_mov_b32_e32 v3, v99
	v_mov_b32_e32 v4, v100
	v_mov_b32_e32 v5, v101
	v_mov_b32_e32 v6, v102
	v_mov_b32_e32 v7, v103
	v_mov_b32_e32 v8, v104
	v_mov_b32_e32 v9, v105
	v_mov_b32_e32 v10, v106
	v_mov_b32_e32 v11, v107
	v_mov_b32_e32 v12, v108
	v_mov_b32_e32 v13, v109
	v_mov_b32_e32 v14, v110
	v_mov_b32_e32 v15, v111
	v_mov_b32_e32 v16, v112
	v_mov_b32_e32 v17, v113
	v_mov_b32_e32 v18, v114
	v_mov_b32_e32 v19, v115
	v_mov_b32_e32 v20, v116
	v_mov_b32_e32 v21, v117
	v_mov_b32_e32 v22, v118
	v_mov_b32_e32 v23, v119
	v_mov_b32_e32 v24, v120
	v_mov_b32_e32 v25, v121
	v_mov_b32_e32 v26, v122
	v_mov_b32_e32 v27, v123
	v_mov_b32_e32 v28, v124
	v_mov_b32_e32 v29, v125
	v_mov_b32_e32 v30, v126
	v_mov_b32_e32 v31, v127
	v_mov_b32_e32 v32, v128
	v_mov_b32_e32 v33, v129
	v_mov_b32_e32 v98, 0
	v_mov_b32_e32 v99, 0
	v_mov_b32_e32 v100, 0
	v_mov_b32_e32 v101, 0
	v_mov_b32_e32 v102, 0
	v_mov_b32_e32 v103, 0
	v_mov_b32_e32 v104, 0
	v_mov_b32_e32 v105, 0
	v_mov_b32_e32 v106, 0
	v_mov_b32_e32 v107, 0
	v_mov_b32_e32 v108, 0
	v_mov_b32_e32 v109, 0
	v_mov_b32_e32 v110, 0
	v_mov_b32_e32 v111, 0
	v_mov_b32_e32 v112, 0
	v_mov_b32_e32 v113, 0
	v_mov_b32_e32 v114, 0
	v_mov_b32_e32 v115, 0
	v_mov_b32_e32 v116, 0
	v_mov_b32_e32 v117, 0
	v_mov_b32_e32 v118, 0
	v_mov_b32_e32 v119, 0
	v_mov_b32_e32 v120, 0
	v_mov_b32_e32 v121, 0
	v_mov_b32_e32 v122, 0
	v_mov_b32_e32 v123, 0
	v_mov_b32_e32 v124, 0
	v_mov_b32_e32 v125, 0
	v_mov_b32_e32 v126, 0
	v_mov_b32_e32 v127, 0
	v_mov_b32_e32 v128, 0
	v_mov_b32_e32 v129, 0
	s_branch .Lq_epi
